# P13-epilogue-second-half-loads-issued-with-first-half-loads
# baseline (speedup 1.0000x reference)
; #define GAS __attribute__((address_space(1)))
; __device__ __forceinline__ float sigmoidf_(float x) { return __builtin_amdgcn_rcpf(1.0f + __builtin_amdgcn_exp2f(-1.4426950408889634f * x)); }
; __device__ __forceinline__ void unpack8(v4u w, float (&f)[8]) { f[0] = bflo(w.x); f[1] = bfhi(w.x); f[2] = bflo(w.y); f[3] = bfhi(w.y); f[4] = bflo(w.z); f[5] = bfhi(w.z); f[6] = bflo(w.w); f[7] = bfhi(w.w); }
; __device__ __forceinline__ float row_rs(const float* SS, int row) {
;     const f32x4 a = *(const GAS f32x4*)(SS + (size_t)row * 16), b = *(const GAS f32x4*)(SS + (size_t)row * 16 + 4), c = *(const GAS f32x4*)(SS + (size_t)row * 16 + 8), d = *(const GAS f32x4*)(SS + (size_t)row * 16 + 12);
;     const float s = ((a[0] + a[1]) + (a[2] + a[3])) + ((b[0] + b[1]) + (b[2] + b[3])) + ((c[0] + c[1]) + (c[2] + c[3])) + ((d[0] + d[1]) + (d[2] + d[3]));
;     return __builtin_amdgcn_rsqf(s * (1.f / D) + EPS);
;     __device__ __forceinline__ void operator()(const pg8::f32x4 (&acc)[2][2][4][2], const pg8::Unit& u, int wr, int wc, int fr, int fq) const {
;         const int row0 = u.pm * 256 + wr * 64 + fr, col0 = u.pn * 256 + wc * 32 + 8 * fq;
; #pragma unroll
;         for (int ai = 0; ai < 2; ++ai)
; #pragma unroll
;             for (int m = 0; m < 4; ++m) { if (u.q >= 0 && m != u.q) continue; const int row = row0 + ai * 128 + m * 16; const float rs = row_rs(SS, row);
; #pragma unroll
;                 for (int bj = 0; bj < 2; ++bj) { const int col = col0 + bj * 128; const size_t o = (size_t)row * D + col;
;                     float pw[8], xw[8]; unpack8(*(const GAS v4u*)(PPB + o), pw); unpack8(*(const GAS v4u*)(X2B + o), xw);
;                     const f32x4 a = acc[ai][bj][m][0] * rs, b = acc[ai][bj][m][1] * rs; f32x4 y0, y1;
; #pragma unroll
;                     for (int i = 0; i < 4; ++i) { y0[i] = xw[i] + sigmoidf_(a[i]) * pw[i]; y1[i] = xw[4 + i] + sigmoidf_(b[i]) * pw[4 + i]; }
;                     *(GAS f32x4*)(Y + o) = y0; *(GAS f32x4*)(Y + o + 4) = y1; } }
.LBB0_3294:
	v_lshl_add_u32 v150, s16, 8, v1
	v_ashrrev_i32_e32 v151, 31, v150
	v_lshlrev_b64 v[146:147], 6, v[150:151]
	v_lshl_add_u64 v[146:147], s[12:13], 0, v[146:147]
	global_load_dwordx4 v[158:161], v[146:147], off
	global_load_dwordx4 v[162:165], v[146:147], off offset:16
	global_load_dwordx4 v[166:169], v[146:147], off offset:32
	global_load_dwordx4 v[170:173], v[146:147], off offset:48
	v_lshl_or_b32 v146, s52, 8, v153
	v_ashrrev_i32_e32 v147, 31, v146
	v_lshlrev_b64 v[182:183], 10, v[150:151]
	v_lshl_add_u64 v[184:185], v[182:183], 0, v[146:147]
	v_lshlrev_b64 v[148:149], 1, v[184:185]
	v_lshl_add_u64 v[174:175], s[14:15], 0, v[148:149]
	v_lshl_add_u64 v[148:149], s[10:11], 0, v[148:149]
	global_load_dwordx4 v[174:177], v[174:175], off
	v_readlane_b32 s52, v254, 63
	global_load_dwordx4 v[178:181], v[148:149], off
	v_or_b32_e32 v148, 0x80, v146
	v_ashrrev_i32_e32 v149, 31, v148
	v_readlane_b32 s66, v255, 13
	v_readlane_b32 s67, v255, 14
	v_lshl_add_u64 v[182:183], v[182:183], 0, v[148:149]
	s_mov_b64 s[30:31], s[66:67]
	v_lshl_add_u64 v[184:185], v[184:185], 2, s[30:31]
	v_lshlrev_b64 v[182:183], 1, v[182:183]
	v_lshl_add_u64 v[186:187], s[14:15], 0, v[182:183]
	s_andn2_b64 vcc, exec, s[2:3]
	s_mov_b64 s[2:3], -1
	v_readlane_b32 s53, v255, 0
	v_readlane_b32 s54, v255, 1
	v_readlane_b32 s55, v255, 2
	v_readlane_b32 s56, v255, 3
	v_readlane_b32 s57, v255, 4
	v_readlane_b32 s58, v255, 5
	v_readlane_b32 s59, v255, 6
	v_readlane_b32 s60, v255, 7
	v_readlane_b32 s61, v255, 8
	v_readlane_b32 s62, v255, 9
	v_readlane_b32 s63, v255, 10
	v_readlane_b32 s64, v255, 11
	v_readlane_b32 s65, v255, 12
	v_lshl_add_u64 v[198:199], s[10:11], 0, v[182:183]
	global_load_dwordx4 v[190:193], v[186:187], off
	global_load_dwordx4 v[194:197], v[198:199], off
	s_waitcnt vmcnt(0)
	v_mov_b32_e32 v188, v159
	v_mov_b32_e32 v189, v160
	v_mov_b32_e32 v159, v161
	v_mov_b32_e32 v160, v163
	v_mov_b32_e32 v161, v164
	v_mov_b32_e32 v163, v165
	v_pk_add_f32 v[158:159], v[188:189], v[158:159]
	v_pk_add_f32 v[160:161], v[160:161], v[162:163]
	v_pk_add_f32 v[158:159], v[158:159], v[158:159] op_sel:[0,1] op_sel_hi:[1,0]
	v_pk_add_f32 v[160:161], v[160:161], v[160:161] op_sel:[0,1] op_sel_hi:[1,0]
	v_add_f32_e32 v164, v166, v167
	v_add_f32_e32 v166, v168, v169
	v_mov_b32_e32 v165, v172
	v_mov_b32_e32 v167, v173
	v_mov_b32_e32 v159, v170
	v_mov_b32_e32 v161, v171
	v_pk_add_f32 v[162:163], v[164:165], v[166:167]
	v_pk_add_f32 v[158:159], v[158:159], v[160:161]
	v_lshlrev_b32_e32 v164, 16, v174
	v_pk_add_f32 v[158:159], v[158:159], v[162:163]
	v_and_b32_e32 v165, 0xffff0000, v174
	v_add_f32_e32 v151, v158, v159
	v_fmamk_f32 v151, v151, 0x3a800000, v157
	v_rsq_f32_e32 v151, v151
	v_lshlrev_b32_e32 v166, 16, v178
	v_and_b32_e32 v167, 0xffff0000, v178
	v_lshlrev_b32_e32 v168, 16, v176
	v_mul_f32_e32 v122, v122, v151
	v_mul_f32_e32 v126, v126, v151
	v_mul_f32_e32 v123, v123, v151
	v_mul_f32_e32 v127, v127, v151
	v_mul_f32_e32 v124, v124, v151
	v_mul_f32_e32 v125, v125, v151
	v_mul_f32_e32 v128, v128, v151
	v_mul_f32_e32 v129, v129, v151
	v_mul_f32_e32 v122, 0xbfb8aa3b, v122
	v_mul_f32_e32 v126, 0xbfb8aa3b, v126
	v_mul_f32_e32 v123, 0xbfb8aa3b, v123
	v_mul_f32_e32 v127, 0xbfb8aa3b, v127
	v_mul_f32_e32 v124, 0xbfb8aa3b, v124
	v_mul_f32_e32 v125, 0xbfb8aa3b, v125
	v_mul_f32_e32 v128, 0xbfb8aa3b, v128
	v_mul_f32_e32 v129, 0xbfb8aa3b, v129
	v_exp_f32_e32 v122, v122
	v_exp_f32_e32 v126, v126
	v_exp_f32_e32 v123, v123
	v_exp_f32_e32 v127, v127
	v_exp_f32_e32 v124, v124
	v_exp_f32_e32 v125, v125
	v_exp_f32_e32 v128, v128
	v_exp_f32_e32 v129, v129
	v_add_f32_e32 v122, 1.0, v122
	v_add_f32_e32 v126, 1.0, v126
	v_add_f32_e32 v123, 1.0, v123
	v_add_f32_e32 v127, 1.0, v127
	v_add_f32_e32 v160, 1.0, v124
	v_add_f32_e32 v162, 1.0, v125
	v_add_f32_e32 v161, 1.0, v128
	v_add_f32_e32 v163, 1.0, v129
	v_rcp_f32_e32 v122, v122
	v_rcp_f32_e32 v124, v126
	v_rcp_f32_e32 v123, v123
	v_rcp_f32_e32 v125, v127
	v_rcp_f32_e32 v128, v160
	v_rcp_f32_e32 v129, v162
	v_rcp_f32_e32 v160, v161
	v_rcp_f32_e32 v161, v163
	v_and_b32_e32 v169, 0xffff0000, v176
	v_lshlrev_b32_e32 v172, 16, v180
	v_and_b32_e32 v173, 0xffff0000, v180
	v_lshlrev_b32_e32 v174, 16, v175
	v_and_b32_e32 v175, 0xffff0000, v175
	v_lshlrev_b32_e32 v178, 16, v179
	v_and_b32_e32 v179, 0xffff0000, v179
	v_lshlrev_b32_e32 v176, 16, v177
	v_and_b32_e32 v177, 0xffff0000, v177
	v_lshlrev_b32_e32 v158, 16, v181
	v_and_b32_e32 v159, 0xffff0000, v181
	v_pk_fma_f32 v[122:123], v[122:123], v[164:165], v[166:167]
	v_pk_fma_f32 v[126:127], v[124:125], v[168:169], v[172:173]
	v_pk_fma_f32 v[124:125], v[128:129], v[174:175], v[178:179]
	v_pk_fma_f32 v[128:129], v[160:161], v[176:177], v[158:159]
	global_store_dwordx4 v[184:185], v[122:125], off
	global_store_dwordx4 v[184:185], v[126:129], off offset:16
	v_mul_f32_e32 v118, v118, v151
	v_mul_f32_e32 v114, v114, v151
	v_mul_f32_e32 v119, v119, v151
	v_mul_f32_e32 v115, v115, v151
	v_mul_f32_e32 v120, v120, v151
	v_mul_f32_e32 v121, v121, v151
	v_mul_f32_e32 v116, v116, v151
	v_mul_f32_e32 v117, v117, v151
	v_mul_f32_e32 v118, 0xbfb8aa3b, v118
	v_mul_f32_e32 v114, 0xbfb8aa3b, v114
	v_mul_f32_e32 v119, 0xbfb8aa3b, v119
	v_mul_f32_e32 v115, 0xbfb8aa3b, v115
	v_mul_f32_e32 v120, 0xbfb8aa3b, v120
	v_mul_f32_e32 v121, 0xbfb8aa3b, v121
	v_mul_f32_e32 v116, 0xbfb8aa3b, v116
	v_mul_f32_e32 v117, 0xbfb8aa3b, v117
	v_exp_f32_e32 v118, v118
	v_exp_f32_e32 v114, v114
	v_exp_f32_e32 v119, v119
	v_exp_f32_e32 v115, v115
	v_exp_f32_e32 v120, v120
	v_exp_f32_e32 v121, v121
	v_exp_f32_e32 v116, v116
	v_exp_f32_e32 v117, v117
	v_add_f32_e32 v118, 1.0, v118
	v_add_f32_e32 v151, 1.0, v114
	v_add_f32_e32 v119, 1.0, v119
	v_add_f32_e32 v162, 1.0, v115
	v_add_f32_e32 v120, 1.0, v120
	v_add_f32_e32 v121, 1.0, v121
	v_add_f32_e32 v163, 1.0, v116
	v_add_f32_e32 v164, 1.0, v117
	v_rcp_f32_e32 v114, v118
	v_rcp_f32_e32 v116, v151
	v_rcp_f32_e32 v115, v119
	v_rcp_f32_e32 v117, v162
	v_rcp_f32_e32 v120, v120
	v_rcp_f32_e32 v121, v121
	v_rcp_f32_e32 v162, v163
	v_rcp_f32_e32 v163, v164
	v_or_b32_e32 v158, 16, v150
	v_ashrrev_i32_e32 v159, 31, v158
	v_lshlrev_b64 v[160:161], 6, v[158:159]
	v_lshl_add_u64 v[160:161], s[12:13], 0, v[160:161]
	s_waitcnt vmcnt(2)
; #define GAS __attribute__((address_space(1)))
; __device__ __forceinline__ float sigmoidf_(float x) { return __builtin_amdgcn_rcpf(1.0f + __builtin_amdgcn_exp2f(-1.4426950408889634f * x)); }
; __device__ __forceinline__ void unpack8(v4u w, float (&f)[8]) { f[0] = bflo(w.x); f[1] = bfhi(w.x); f[2] = bflo(w.y); f[3] = bfhi(w.y); f[4] = bflo(w.z); f[5] = bfhi(w.z); f[6] = bflo(w.w); f[7] = bfhi(w.w); }
; __device__ __forceinline__ float row_rs(const float* SS, int row) {
;     const f32x4 a = *(const GAS f32x4*)(SS + (size_t)row * 16), b = *(const GAS f32x4*)(SS + (size_t)row * 16 + 4), c = *(const GAS f32x4*)(SS + (size_t)row * 16 + 8), d = *(const GAS f32x4*)(SS + (size_t)row * 16 + 12);
;     const float s = ((a[0] + a[1]) + (a[2] + a[3])) + ((b[0] + b[1]) + (b[2] + b[3])) + ((c[0] + c[1]) + (c[2] + c[3])) + ((d[0] + d[1]) + (d[2] + d[3]));
;     return __builtin_amdgcn_rsqf(s * (1.f / D) + EPS);
;     __device__ __forceinline__ void operator()(const pg8::f32x4 (&acc)[2][2][4][2], const pg8::Unit& u, int wr, int wc, int fr, int fq) const {
;         const int row0 = u.pm * 256 + wr * 64 + fr, col0 = u.pn * 256 + wc * 32 + 8 * fq;
; #pragma unroll
;         for (int ai = 0; ai < 2; ++ai)
; #pragma unroll
;             for (int m = 0; m < 4; ++m) { if (u.q >= 0 && m != u.q) continue; const int row = row0 + ai * 128 + m * 16; const float rs = row_rs(SS, row);
; #pragma unroll
;                 for (int bj = 0; bj < 2; ++bj) { const int col = col0 + bj * 128; const size_t o = (size_t)row * D + col;
;                     float pw[8], xw[8]; unpack8(*(const GAS v4u*)(PPB + o), pw); unpack8(*(const GAS v4u*)(X2B + o), xw);
;                     const f32x4 a = acc[ai][bj][m][0] * rs, b = acc[ai][bj][m][1] * rs; f32x4 y0, y1;
; #pragma unroll
;                     for (int i = 0; i < 4; ++i) { y0[i] = xw[i] + sigmoidf_(a[i]) * pw[i]; y1[i] = xw[4 + i] + sigmoidf_(b[i]) * pw[4 + i]; }
;                     *(GAS f32x4*)(Y + o) = y0; *(GAS f32x4*)(Y + o + 4) = y1; } }
	v_lshlrev_b32_e32 v118, 16, v190
	v_and_b32_e32 v119, 0xffff0000, v190
	v_lshlrev_b32_e32 v166, 16, v192
	v_lshlrev_b32_e32 v164, 16, v194
	v_and_b32_e32 v165, 0xffff0000, v194
	v_and_b32_e32 v167, 0xffff0000, v192
	v_lshlrev_b32_e32 v168, 16, v196
	v_and_b32_e32 v169, 0xffff0000, v196
	v_lshlrev_b32_e32 v122, 16, v191
	v_and_b32_e32 v123, 0xffff0000, v191
	v_lshlrev_b32_e32 v126, 16, v195
	v_and_b32_e32 v127, 0xffff0000, v195
	v_lshlrev_b32_e32 v124, 16, v193
	v_and_b32_e32 v125, 0xffff0000, v193
	v_lshlrev_b32_e32 v128, 16, v197
	v_and_b32_e32 v129, 0xffff0000, v197
	v_pk_fma_f32 v[114:115], v[114:115], v[118:119], v[164:165]
	v_pk_fma_f32 v[118:119], v[116:117], v[166:167], v[168:169]
	v_pk_fma_f32 v[116:117], v[120:121], v[122:123], v[126:127]
	v_pk_fma_f32 v[120:121], v[162:163], v[124:125], v[128:129]
	global_store_dwordx4 v[184:185], v[114:117], off offset:512
	global_store_dwordx4 v[184:185], v[118:121], off offset:528
	global_load_dwordx4 v[114:117], v[160:161], off
	s_nop 0
	global_load_dwordx4 v[118:121], v[160:161], off offset:16
	global_load_dwordx4 v[122:125], v[160:161], off offset:48
	global_load_dwordx4 v[126:129], v[160:161], off offset:32
	v_lshlrev_b64 v[166:167], 10, v[158:159]
	v_lshl_add_u64 v[168:169], v[166:167], 0, v[146:147]
	v_lshlrev_b64 v[162:163], 1, v[168:169]
	v_lshl_add_u64 v[158:159], s[14:15], 0, v[162:163]
	v_lshl_add_u64 v[162:163], s[10:11], 0, v[162:163]
	global_load_dwordx4 v[158:161], v[158:159], off
	v_lshl_add_u64 v[166:167], v[166:167], 0, v[148:149]
	global_load_dwordx4 v[162:165], v[162:163], off
	v_lshl_add_u64 v[168:169], v[168:169], 2, s[30:31]
	v_lshlrev_b64 v[166:167], 1, v[166:167]
	v_lshl_add_u64 v[170:171], s[14:15], 0, v[166:167]
	v_lshl_add_u64 v[198:199], s[10:11], 0, v[166:167]
	global_load_dwordx4 v[190:193], v[170:171], off
	global_load_dwordx4 v[194:197], v[198:199], off
	s_waitcnt vmcnt(0)
	v_mov_b32_e32 v172, v115
	v_mov_b32_e32 v173, v116
	v_mov_b32_e32 v115, v117
	v_mov_b32_e32 v116, v119
	v_mov_b32_e32 v117, v120
	v_mov_b32_e32 v119, v121
	v_pk_add_f32 v[114:115], v[172:173], v[114:115]
	v_pk_add_f32 v[116:117], v[116:117], v[118:119]
	v_pk_add_f32 v[114:115], v[114:115], v[114:115] op_sel:[0,1] op_sel_hi:[1,0]
	v_pk_add_f32 v[116:117], v[116:117], v[116:117] op_sel:[0,1] op_sel_hi:[1,0]
	v_add_f32_e32 v120, v126, v127
	v_add_f32_e32 v126, v128, v129
	v_mov_b32_e32 v121, v124
	v_mov_b32_e32 v127, v125
	v_mov_b32_e32 v115, v122
	v_mov_b32_e32 v117, v123
	v_pk_add_f32 v[118:119], v[120:121], v[126:127]
	v_pk_add_f32 v[114:115], v[114:115], v[116:117]
	v_lshlrev_b32_e32 v124, 16, v158
	v_pk_add_f32 v[114:115], v[114:115], v[118:119]
	v_and_b32_e32 v125, 0xffff0000, v158
	v_add_f32_e32 v114, v114, v115
	v_fmamk_f32 v114, v114, 0x3a800000, v157
	v_rsq_f32_e32 v118, v114
	v_lshlrev_b32_e32 v128, 16, v162
	v_and_b32_e32 v129, 0xffff0000, v162
	v_lshlrev_b32_e32 v174, 16, v160
	v_mul_f32_e32 v110, v110, v118
	v_mul_f32_e32 v106, v106, v118
	v_mul_f32_e32 v111, v111, v118
	v_mul_f32_e32 v107, v107, v118
	v_mul_f32_e32 v112, v112, v118
	v_mul_f32_e32 v113, v113, v118
	v_mul_f32_e32 v108, v108, v118
	v_mul_f32_e32 v109, v109, v118
	v_mul_f32_e32 v110, 0xbfb8aa3b, v110
	v_mul_f32_e32 v106, 0xbfb8aa3b, v106
	v_mul_f32_e32 v111, 0xbfb8aa3b, v111
	v_mul_f32_e32 v107, 0xbfb8aa3b, v107
	v_mul_f32_e32 v112, 0xbfb8aa3b, v112
	v_mul_f32_e32 v113, 0xbfb8aa3b, v113
	v_mul_f32_e32 v108, 0xbfb8aa3b, v108
	v_mul_f32_e32 v109, 0xbfb8aa3b, v109
	v_exp_f32_e32 v110, v110
	v_exp_f32_e32 v106, v106
	v_exp_f32_e32 v111, v111
	v_exp_f32_e32 v107, v107
	v_exp_f32_e32 v112, v112
	v_exp_f32_e32 v113, v113
	v_exp_f32_e32 v108, v108
	v_exp_f32_e32 v109, v109
	v_add_f32_e32 v110, 1.0, v110
	v_add_f32_e32 v116, 1.0, v106
	v_add_f32_e32 v111, 1.0, v111
	v_add_f32_e32 v117, 1.0, v107
	v_add_f32_e32 v112, 1.0, v112
	v_add_f32_e32 v113, 1.0, v113
	v_add_f32_e32 v119, 1.0, v108
	v_add_f32_e32 v120, 1.0, v109
	v_rcp_f32_e32 v106, v110
	v_rcp_f32_e32 v108, v116
	v_rcp_f32_e32 v107, v111
	v_rcp_f32_e32 v109, v117
	v_rcp_f32_e32 v112, v112
	v_rcp_f32_e32 v113, v113
	v_rcp_f32_e32 v116, v119
	v_rcp_f32_e32 v117, v120
	v_and_b32_e32 v175, 0xffff0000, v160
	v_lshlrev_b32_e32 v176, 16, v164
	v_and_b32_e32 v177, 0xffff0000, v164
	v_lshlrev_b32_e32 v158, 16, v159
	v_and_b32_e32 v159, 0xffff0000, v159
	v_lshlrev_b32_e32 v162, 16, v163
	v_and_b32_e32 v163, 0xffff0000, v163
	v_lshlrev_b32_e32 v160, 16, v161
	v_and_b32_e32 v161, 0xffff0000, v161
	v_lshlrev_b32_e32 v114, 16, v165
	v_and_b32_e32 v115, 0xffff0000, v165
	v_pk_fma_f32 v[106:107], v[106:107], v[124:125], v[128:129]
	v_pk_fma_f32 v[110:111], v[108:109], v[174:175], v[176:177]
	v_pk_fma_f32 v[108:109], v[112:113], v[158:159], v[162:163]
	v_pk_fma_f32 v[112:113], v[116:117], v[160:161], v[114:115]
	global_store_dwordx4 v[168:169], v[106:109], off
	global_store_dwordx4 v[168:169], v[110:113], off offset:16
	v_mul_f32_e32 v102, v102, v118
	v_mul_f32_e32 v98, v98, v118
	v_mul_f32_e32 v103, v103, v118
	v_mul_f32_e32 v99, v99, v118
	v_mul_f32_e32 v104, v104, v118
	v_mul_f32_e32 v105, v105, v118
	v_mul_f32_e32 v100, v100, v118
	v_mul_f32_e32 v101, v101, v118
	v_mul_f32_e32 v102, 0xbfb8aa3b, v102
	v_mul_f32_e32 v98, 0xbfb8aa3b, v98
	v_mul_f32_e32 v103, 0xbfb8aa3b, v103
	v_mul_f32_e32 v99, 0xbfb8aa3b, v99
	v_mul_f32_e32 v104, 0xbfb8aa3b, v104
	v_mul_f32_e32 v105, 0xbfb8aa3b, v105
	v_mul_f32_e32 v100, 0xbfb8aa3b, v100
	v_mul_f32_e32 v101, 0xbfb8aa3b, v101
	v_exp_f32_e32 v102, v102
	v_exp_f32_e32 v98, v98
	v_exp_f32_e32 v103, v103
	v_exp_f32_e32 v99, v99
	v_exp_f32_e32 v104, v104
	v_exp_f32_e32 v105, v105
	v_exp_f32_e32 v100, v100
	v_exp_f32_e32 v101, v101
	v_add_f32_e32 v102, 1.0, v102
	v_add_f32_e32 v118, 1.0, v98
	v_add_f32_e32 v103, 1.0, v103
	v_add_f32_e32 v119, 1.0, v99
	v_add_f32_e32 v104, 1.0, v104
	v_add_f32_e32 v105, 1.0, v105
	v_add_f32_e32 v120, 1.0, v100
	v_add_f32_e32 v121, 1.0, v101
	v_rcp_f32_e32 v98, v102
	v_rcp_f32_e32 v100, v118
	v_rcp_f32_e32 v99, v103
	v_rcp_f32_e32 v101, v119
	v_rcp_f32_e32 v104, v104
	v_rcp_f32_e32 v105, v105
	v_rcp_f32_e32 v118, v120
	v_rcp_f32_e32 v119, v121
	v_or_b32_e32 v114, 32, v150
	v_ashrrev_i32_e32 v115, 31, v114
	v_lshlrev_b64 v[116:117], 6, v[114:115]
	v_lshl_add_u64 v[116:117], s[12:13], 0, v[116:117]
	s_waitcnt vmcnt(2)
; #define GAS __attribute__((address_space(1)))
; __device__ __forceinline__ float sigmoidf_(float x) { return __builtin_amdgcn_rcpf(1.0f + __builtin_amdgcn_exp2f(-1.4426950408889634f * x)); }
; __device__ __forceinline__ void unpack8(v4u w, float (&f)[8]) { f[0] = bflo(w.x); f[1] = bfhi(w.x); f[2] = bflo(w.y); f[3] = bfhi(w.y); f[4] = bflo(w.z); f[5] = bfhi(w.z); f[6] = bflo(w.w); f[7] = bfhi(w.w); }
; __device__ __forceinline__ float row_rs(const float* SS, int row) {
;     const f32x4 a = *(const GAS f32x4*)(SS + (size_t)row * 16), b = *(const GAS f32x4*)(SS + (size_t)row * 16 + 4), c = *(const GAS f32x4*)(SS + (size_t)row * 16 + 8), d = *(const GAS f32x4*)(SS + (size_t)row * 16 + 12);
;     const float s = ((a[0] + a[1]) + (a[2] + a[3])) + ((b[0] + b[1]) + (b[2] + b[3])) + ((c[0] + c[1]) + (c[2] + c[3])) + ((d[0] + d[1]) + (d[2] + d[3]));
;     return __builtin_amdgcn_rsqf(s * (1.f / D) + EPS);
;     __device__ __forceinline__ void operator()(const pg8::f32x4 (&acc)[2][2][4][2], const pg8::Unit& u, int wr, int wc, int fr, int fq) const {
;         const int row0 = u.pm * 256 + wr * 64 + fr, col0 = u.pn * 256 + wc * 32 + 8 * fq;
; #pragma unroll
;         for (int ai = 0; ai < 2; ++ai)
; #pragma unroll
;             for (int m = 0; m < 4; ++m) { if (u.q >= 0 && m != u.q) continue; const int row = row0 + ai * 128 + m * 16; const float rs = row_rs(SS, row);
; #pragma unroll
;                 for (int bj = 0; bj < 2; ++bj) { const int col = col0 + bj * 128; const size_t o = (size_t)row * D + col;
;                     float pw[8], xw[8]; unpack8(*(const GAS v4u*)(PPB + o), pw); unpack8(*(const GAS v4u*)(X2B + o), xw);
;                     const f32x4 a = acc[ai][bj][m][0] * rs, b = acc[ai][bj][m][1] * rs; f32x4 y0, y1;
; #pragma unroll
;                     for (int i = 0; i < 4; ++i) { y0[i] = xw[i] + sigmoidf_(a[i]) * pw[i]; y1[i] = xw[4 + i] + sigmoidf_(b[i]) * pw[4 + i]; }
;                     *(GAS f32x4*)(Y + o) = y0; *(GAS f32x4*)(Y + o + 4) = y1; } }
	v_lshlrev_b32_e32 v102, 16, v190
	v_and_b32_e32 v103, 0xffff0000, v190
	v_lshlrev_b32_e32 v122, 16, v192
	v_lshlrev_b32_e32 v120, 16, v194
	v_and_b32_e32 v121, 0xffff0000, v194
	v_and_b32_e32 v123, 0xffff0000, v192
	v_lshlrev_b32_e32 v124, 16, v196
	v_and_b32_e32 v125, 0xffff0000, v196
	v_lshlrev_b32_e32 v106, 16, v191
	v_and_b32_e32 v107, 0xffff0000, v191
	v_lshlrev_b32_e32 v110, 16, v195
	v_and_b32_e32 v111, 0xffff0000, v195
	v_lshlrev_b32_e32 v108, 16, v193
	v_and_b32_e32 v109, 0xffff0000, v193
	v_lshlrev_b32_e32 v112, 16, v197
	v_and_b32_e32 v113, 0xffff0000, v197
	v_pk_fma_f32 v[98:99], v[98:99], v[102:103], v[120:121]
	v_pk_fma_f32 v[102:103], v[100:101], v[122:123], v[124:125]
	v_pk_fma_f32 v[100:101], v[104:105], v[106:107], v[110:111]
	v_pk_fma_f32 v[104:105], v[118:119], v[108:109], v[112:113]
	global_store_dwordx4 v[168:169], v[98:101], off offset:512
	global_store_dwordx4 v[168:169], v[102:105], off offset:528
	global_load_dwordx4 v[98:101], v[116:117], off
	s_nop 0
	global_load_dwordx4 v[102:105], v[116:117], off offset:16
	global_load_dwordx4 v[106:109], v[116:117], off offset:48
	global_load_dwordx4 v[110:113], v[116:117], off offset:32
	v_lshlrev_b64 v[122:123], 10, v[114:115]
	v_lshl_add_u64 v[124:125], v[122:123], 0, v[146:147]
	v_lshlrev_b64 v[118:119], 1, v[124:125]
	v_lshl_add_u64 v[114:115], s[14:15], 0, v[118:119]
	v_lshl_add_u64 v[118:119], s[10:11], 0, v[118:119]
	global_load_dwordx4 v[114:117], v[114:115], off
	v_lshl_add_u64 v[122:123], v[122:123], 0, v[148:149]
	global_load_dwordx4 v[118:121], v[118:119], off
	v_lshl_add_u64 v[124:125], v[124:125], 2, s[30:31]
	v_lshlrev_b64 v[122:123], 1, v[122:123]
	v_lshl_add_u64 v[126:127], s[14:15], 0, v[122:123]
	v_lshl_add_u64 v[198:199], s[10:11], 0, v[122:123]
	global_load_dwordx4 v[190:193], v[126:127], off
	global_load_dwordx4 v[194:197], v[198:199], off
	s_waitcnt vmcnt(0)
	v_mov_b32_e32 v128, v99
	v_mov_b32_e32 v129, v100
	v_mov_b32_e32 v99, v101
	v_mov_b32_e32 v100, v103
	v_mov_b32_e32 v101, v104
	v_mov_b32_e32 v103, v105
	v_pk_add_f32 v[98:99], v[128:129], v[98:99]
	v_pk_add_f32 v[100:101], v[100:101], v[102:103]
	v_pk_add_f32 v[98:99], v[98:99], v[98:99] op_sel:[0,1] op_sel_hi:[1,0]
	v_pk_add_f32 v[100:101], v[100:101], v[100:101] op_sel:[0,1] op_sel_hi:[1,0]
	v_add_f32_e32 v104, v110, v111
	v_add_f32_e32 v110, v112, v113
	v_mov_b32_e32 v105, v108
	v_mov_b32_e32 v111, v109
	v_mov_b32_e32 v99, v106
	v_mov_b32_e32 v101, v107
	v_pk_add_f32 v[102:103], v[104:105], v[110:111]
	v_pk_add_f32 v[98:99], v[98:99], v[100:101]
	v_lshlrev_b32_e32 v108, 16, v114
	v_pk_add_f32 v[98:99], v[98:99], v[102:103]
	v_and_b32_e32 v109, 0xffff0000, v114
	v_add_f32_e32 v98, v98, v99
	v_fmamk_f32 v98, v98, 0x3a800000, v157
	v_rsq_f32_e32 v102, v98
	v_lshlrev_b32_e32 v112, 16, v118
	v_and_b32_e32 v113, 0xffff0000, v118
	v_lshlrev_b32_e32 v158, 16, v116
	v_mul_f32_e32 v94, v94, v102
	v_mul_f32_e32 v90, v90, v102
	v_mul_f32_e32 v95, v95, v102
	v_mul_f32_e32 v91, v91, v102
	v_mul_f32_e32 v96, v96, v102
	v_mul_f32_e32 v97, v97, v102
	v_mul_f32_e32 v92, v92, v102
	v_mul_f32_e32 v93, v93, v102
	v_mul_f32_e32 v94, 0xbfb8aa3b, v94
	v_mul_f32_e32 v90, 0xbfb8aa3b, v90
	v_mul_f32_e32 v95, 0xbfb8aa3b, v95
	v_mul_f32_e32 v91, 0xbfb8aa3b, v91
	v_mul_f32_e32 v96, 0xbfb8aa3b, v96
	v_mul_f32_e32 v97, 0xbfb8aa3b, v97
	v_mul_f32_e32 v92, 0xbfb8aa3b, v92
	v_mul_f32_e32 v93, 0xbfb8aa3b, v93
	v_exp_f32_e32 v94, v94
	v_exp_f32_e32 v90, v90
	v_exp_f32_e32 v95, v95
	v_exp_f32_e32 v91, v91
	v_exp_f32_e32 v96, v96
	v_exp_f32_e32 v97, v97
	v_exp_f32_e32 v92, v92
	v_exp_f32_e32 v93, v93
	v_add_f32_e32 v94, 1.0, v94
	v_add_f32_e32 v100, 1.0, v90
	v_add_f32_e32 v95, 1.0, v95
	v_add_f32_e32 v101, 1.0, v91
	v_add_f32_e32 v96, 1.0, v96
	v_add_f32_e32 v97, 1.0, v97
	v_add_f32_e32 v103, 1.0, v92
	v_add_f32_e32 v104, 1.0, v93
	v_rcp_f32_e32 v90, v94
	v_rcp_f32_e32 v92, v100
	v_rcp_f32_e32 v91, v95
	v_rcp_f32_e32 v93, v101
	v_rcp_f32_e32 v96, v96
	v_rcp_f32_e32 v97, v97
	v_rcp_f32_e32 v100, v103
	v_rcp_f32_e32 v101, v104
	v_and_b32_e32 v159, 0xffff0000, v116
	v_lshlrev_b32_e32 v160, 16, v120
	v_and_b32_e32 v161, 0xffff0000, v120
	v_lshlrev_b32_e32 v114, 16, v115
	v_and_b32_e32 v115, 0xffff0000, v115
	v_lshlrev_b32_e32 v118, 16, v119
	v_and_b32_e32 v119, 0xffff0000, v119
	v_lshlrev_b32_e32 v116, 16, v117
	v_and_b32_e32 v117, 0xffff0000, v117
	v_lshlrev_b32_e32 v98, 16, v121
	v_and_b32_e32 v99, 0xffff0000, v121
	v_pk_fma_f32 v[90:91], v[90:91], v[108:109], v[112:113]
	v_pk_fma_f32 v[94:95], v[92:93], v[158:159], v[160:161]
	v_pk_fma_f32 v[92:93], v[96:97], v[114:115], v[118:119]
	v_pk_fma_f32 v[96:97], v[100:101], v[116:117], v[98:99]
	global_store_dwordx4 v[124:125], v[90:93], off
	global_store_dwordx4 v[124:125], v[94:97], off offset:16
	v_mul_f32_e32 v86, v86, v102
	v_mul_f32_e32 v82, v82, v102
	v_mul_f32_e32 v87, v87, v102
	v_mul_f32_e32 v83, v83, v102
	v_mul_f32_e32 v88, v88, v102
	v_mul_f32_e32 v89, v89, v102
	v_mul_f32_e32 v84, v84, v102
	v_mul_f32_e32 v85, v85, v102
	v_mul_f32_e32 v86, 0xbfb8aa3b, v86
	v_mul_f32_e32 v82, 0xbfb8aa3b, v82
	v_mul_f32_e32 v87, 0xbfb8aa3b, v87
	v_mul_f32_e32 v83, 0xbfb8aa3b, v83
	v_mul_f32_e32 v88, 0xbfb8aa3b, v88
	v_mul_f32_e32 v89, 0xbfb8aa3b, v89
	v_mul_f32_e32 v84, 0xbfb8aa3b, v84
	v_mul_f32_e32 v85, 0xbfb8aa3b, v85
	v_exp_f32_e32 v86, v86
	v_exp_f32_e32 v82, v82
	v_exp_f32_e32 v87, v87
	v_exp_f32_e32 v83, v83
	v_exp_f32_e32 v88, v88
	v_exp_f32_e32 v89, v89
	v_exp_f32_e32 v84, v84
	v_exp_f32_e32 v85, v85
	v_add_f32_e32 v86, 1.0, v86
	v_add_f32_e32 v102, 1.0, v82
	v_add_f32_e32 v87, 1.0, v87
	v_add_f32_e32 v103, 1.0, v83
	v_add_f32_e32 v88, 1.0, v88
	v_add_f32_e32 v89, 1.0, v89
	v_add_f32_e32 v104, 1.0, v84
	v_add_f32_e32 v105, 1.0, v85
	v_rcp_f32_e32 v82, v86
	v_rcp_f32_e32 v84, v102
	v_rcp_f32_e32 v83, v87
	v_rcp_f32_e32 v85, v103
	v_rcp_f32_e32 v88, v88
	v_rcp_f32_e32 v89, v89
	v_rcp_f32_e32 v102, v104
	v_rcp_f32_e32 v103, v105
	v_or_b32_e32 v98, 48, v150
	v_ashrrev_i32_e32 v99, 31, v98
	v_lshlrev_b64 v[100:101], 6, v[98:99]
	v_lshl_add_u64 v[100:101], s[12:13], 0, v[100:101]
	s_waitcnt vmcnt(2)
; #define GAS __attribute__((address_space(1)))
; __device__ __forceinline__ float sigmoidf_(float x) { return __builtin_amdgcn_rcpf(1.0f + __builtin_amdgcn_exp2f(-1.4426950408889634f * x)); }
; __device__ __forceinline__ void unpack8(v4u w, float (&f)[8]) { f[0] = bflo(w.x); f[1] = bfhi(w.x); f[2] = bflo(w.y); f[3] = bfhi(w.y); f[4] = bflo(w.z); f[5] = bfhi(w.z); f[6] = bflo(w.w); f[7] = bfhi(w.w); }
; __device__ __forceinline__ float row_rs(const float* SS, int row) {
;     const f32x4 a = *(const GAS f32x4*)(SS + (size_t)row * 16), b = *(const GAS f32x4*)(SS + (size_t)row * 16 + 4), c = *(const GAS f32x4*)(SS + (size_t)row * 16 + 8), d = *(const GAS f32x4*)(SS + (size_t)row * 16 + 12);
;     const float s = ((a[0] + a[1]) + (a[2] + a[3])) + ((b[0] + b[1]) + (b[2] + b[3])) + ((c[0] + c[1]) + (c[2] + c[3])) + ((d[0] + d[1]) + (d[2] + d[3]));
;     return __builtin_amdgcn_rsqf(s * (1.f / D) + EPS);
;     __device__ __forceinline__ void operator()(const pg8::f32x4 (&acc)[2][2][4][2], const pg8::Unit& u, int wr, int wc, int fr, int fq) const {
;         const int row0 = u.pm * 256 + wr * 64 + fr, col0 = u.pn * 256 + wc * 32 + 8 * fq;
; #pragma unroll
;         for (int ai = 0; ai < 2; ++ai)
; #pragma unroll
;             for (int m = 0; m < 4; ++m) { if (u.q >= 0 && m != u.q) continue; const int row = row0 + ai * 128 + m * 16; const float rs = row_rs(SS, row);
; #pragma unroll
;                 for (int bj = 0; bj < 2; ++bj) { const int col = col0 + bj * 128; const size_t o = (size_t)row * D + col;
;                     float pw[8], xw[8]; unpack8(*(const GAS v4u*)(PPB + o), pw); unpack8(*(const GAS v4u*)(X2B + o), xw);
;                     const f32x4 a = acc[ai][bj][m][0] * rs, b = acc[ai][bj][m][1] * rs; f32x4 y0, y1;
; #pragma unroll
;                     for (int i = 0; i < 4; ++i) { y0[i] = xw[i] + sigmoidf_(a[i]) * pw[i]; y1[i] = xw[4 + i] + sigmoidf_(b[i]) * pw[4 + i]; }
;                     *(GAS f32x4*)(Y + o) = y0; *(GAS f32x4*)(Y + o + 4) = y1; } }
	v_lshlrev_b32_e32 v86, 16, v190
	v_and_b32_e32 v87, 0xffff0000, v190
	v_lshlrev_b32_e32 v106, 16, v192
	v_lshlrev_b32_e32 v104, 16, v194
	v_and_b32_e32 v105, 0xffff0000, v194
	v_and_b32_e32 v107, 0xffff0000, v192
	v_lshlrev_b32_e32 v108, 16, v196
	v_and_b32_e32 v109, 0xffff0000, v196
	v_lshlrev_b32_e32 v90, 16, v191
	v_and_b32_e32 v91, 0xffff0000, v191
	v_lshlrev_b32_e32 v94, 16, v195
	v_and_b32_e32 v95, 0xffff0000, v195
	v_lshlrev_b32_e32 v92, 16, v193
	v_and_b32_e32 v93, 0xffff0000, v193
	v_lshlrev_b32_e32 v96, 16, v197
	v_and_b32_e32 v97, 0xffff0000, v197
	v_pk_fma_f32 v[82:83], v[82:83], v[86:87], v[104:105]
	v_pk_fma_f32 v[86:87], v[84:85], v[106:107], v[108:109]
	v_pk_fma_f32 v[84:85], v[88:89], v[90:91], v[94:95]
	v_pk_fma_f32 v[88:89], v[102:103], v[92:93], v[96:97]
	global_store_dwordx4 v[124:125], v[82:85], off offset:512
	global_store_dwordx4 v[124:125], v[86:89], off offset:528
	global_load_dwordx4 v[82:85], v[100:101], off
	s_nop 0
	global_load_dwordx4 v[86:89], v[100:101], off offset:16
	global_load_dwordx4 v[90:93], v[100:101], off offset:48
	global_load_dwordx4 v[94:97], v[100:101], off offset:32
	v_lshlrev_b64 v[106:107], 10, v[98:99]
	v_lshl_add_u64 v[108:109], v[106:107], 0, v[146:147]
	v_lshlrev_b64 v[102:103], 1, v[108:109]
	v_lshl_add_u64 v[98:99], s[14:15], 0, v[102:103]
	v_lshl_add_u64 v[102:103], s[10:11], 0, v[102:103]
	global_load_dwordx4 v[98:101], v[98:99], off
	v_lshl_add_u64 v[106:107], v[106:107], 0, v[148:149]
	global_load_dwordx4 v[102:105], v[102:103], off
	v_lshl_add_u64 v[108:109], v[108:109], 2, s[30:31]
	v_lshlrev_b64 v[106:107], 1, v[106:107]
	v_lshl_add_u64 v[110:111], s[14:15], 0, v[106:107]
	v_lshl_add_u64 v[198:199], s[10:11], 0, v[106:107]
	global_load_dwordx4 v[190:193], v[110:111], off
	global_load_dwordx4 v[194:197], v[198:199], off
	s_waitcnt vmcnt(0)
	v_mov_b32_e32 v112, v83
	v_mov_b32_e32 v113, v84
	v_mov_b32_e32 v83, v85
	v_mov_b32_e32 v84, v87
	v_mov_b32_e32 v85, v88
	v_mov_b32_e32 v87, v89
	v_pk_add_f32 v[82:83], v[112:113], v[82:83]
	v_pk_add_f32 v[84:85], v[84:85], v[86:87]
	v_pk_add_f32 v[82:83], v[82:83], v[82:83] op_sel:[0,1] op_sel_hi:[1,0]
	v_pk_add_f32 v[84:85], v[84:85], v[84:85] op_sel:[0,1] op_sel_hi:[1,0]
	v_add_f32_e32 v88, v94, v95
	v_add_f32_e32 v94, v96, v97
	v_mov_b32_e32 v89, v92
	v_mov_b32_e32 v95, v93
	v_mov_b32_e32 v83, v90
	v_mov_b32_e32 v85, v91
	v_pk_add_f32 v[86:87], v[88:89], v[94:95]
	v_pk_add_f32 v[82:83], v[82:83], v[84:85]
	v_lshlrev_b32_e32 v92, 16, v98
	v_pk_add_f32 v[82:83], v[82:83], v[86:87]
	v_and_b32_e32 v93, 0xffff0000, v98
	v_add_f32_e32 v82, v82, v83
	v_fmamk_f32 v82, v82, 0x3a800000, v157
	v_rsq_f32_e32 v86, v82
	v_lshlrev_b32_e32 v96, 16, v102
	v_and_b32_e32 v97, 0xffff0000, v102
	v_lshlrev_b32_e32 v114, 16, v100
	v_mul_f32_e32 v78, v78, v86
	v_mul_f32_e32 v74, v74, v86
	v_mul_f32_e32 v79, v79, v86
	v_mul_f32_e32 v75, v75, v86
	v_mul_f32_e32 v80, v80, v86
	v_mul_f32_e32 v81, v81, v86
	v_mul_f32_e32 v76, v76, v86
	v_mul_f32_e32 v77, v77, v86
	v_mul_f32_e32 v78, 0xbfb8aa3b, v78
	v_mul_f32_e32 v74, 0xbfb8aa3b, v74
	v_mul_f32_e32 v79, 0xbfb8aa3b, v79
	v_mul_f32_e32 v75, 0xbfb8aa3b, v75
	v_mul_f32_e32 v80, 0xbfb8aa3b, v80
	v_mul_f32_e32 v81, 0xbfb8aa3b, v81
	v_mul_f32_e32 v76, 0xbfb8aa3b, v76
	v_mul_f32_e32 v77, 0xbfb8aa3b, v77
	v_exp_f32_e32 v78, v78
	v_exp_f32_e32 v74, v74
	v_exp_f32_e32 v79, v79
	v_exp_f32_e32 v75, v75
	v_exp_f32_e32 v80, v80
	v_exp_f32_e32 v81, v81
	v_exp_f32_e32 v76, v76
	v_exp_f32_e32 v77, v77
	v_add_f32_e32 v78, 1.0, v78
	v_add_f32_e32 v84, 1.0, v74
	v_add_f32_e32 v79, 1.0, v79
	v_add_f32_e32 v85, 1.0, v75
	v_add_f32_e32 v80, 1.0, v80
	v_add_f32_e32 v81, 1.0, v81
	v_add_f32_e32 v87, 1.0, v76
	v_add_f32_e32 v88, 1.0, v77
	v_rcp_f32_e32 v74, v78
	v_rcp_f32_e32 v76, v84
	v_rcp_f32_e32 v75, v79
	v_rcp_f32_e32 v77, v85
	v_rcp_f32_e32 v80, v80
	v_rcp_f32_e32 v81, v81
	v_rcp_f32_e32 v84, v87
	v_rcp_f32_e32 v85, v88
	v_and_b32_e32 v115, 0xffff0000, v100
	v_lshlrev_b32_e32 v116, 16, v104
	v_and_b32_e32 v117, 0xffff0000, v104
	v_lshlrev_b32_e32 v98, 16, v99
	v_and_b32_e32 v99, 0xffff0000, v99
	v_lshlrev_b32_e32 v102, 16, v103
	v_and_b32_e32 v103, 0xffff0000, v103
	v_lshlrev_b32_e32 v100, 16, v101
	v_and_b32_e32 v101, 0xffff0000, v101
	v_lshlrev_b32_e32 v82, 16, v105
	v_and_b32_e32 v83, 0xffff0000, v105
	v_pk_fma_f32 v[74:75], v[74:75], v[92:93], v[96:97]
	v_pk_fma_f32 v[78:79], v[76:77], v[114:115], v[116:117]
	v_pk_fma_f32 v[76:77], v[80:81], v[98:99], v[102:103]
	v_pk_fma_f32 v[80:81], v[84:85], v[100:101], v[82:83]
	global_store_dwordx4 v[108:109], v[74:77], off
	global_store_dwordx4 v[108:109], v[78:81], off offset:16
	v_mul_f32_e32 v70, v70, v86
	v_mul_f32_e32 v66, v66, v86
	v_mul_f32_e32 v71, v71, v86
	v_mul_f32_e32 v67, v67, v86
	v_mul_f32_e32 v72, v72, v86
	v_mul_f32_e32 v73, v73, v86
	v_mul_f32_e32 v68, v68, v86
	v_mul_f32_e32 v69, v69, v86
	v_mul_f32_e32 v70, 0xbfb8aa3b, v70
	v_mul_f32_e32 v66, 0xbfb8aa3b, v66
	v_mul_f32_e32 v71, 0xbfb8aa3b, v71
	v_mul_f32_e32 v67, 0xbfb8aa3b, v67
	v_mul_f32_e32 v72, 0xbfb8aa3b, v72
	v_mul_f32_e32 v73, 0xbfb8aa3b, v73
	v_mul_f32_e32 v68, 0xbfb8aa3b, v68
	v_mul_f32_e32 v69, 0xbfb8aa3b, v69
	v_exp_f32_e32 v70, v70
	v_exp_f32_e32 v66, v66
	v_exp_f32_e32 v71, v71
	v_exp_f32_e32 v67, v67
	v_exp_f32_e32 v72, v72
	v_exp_f32_e32 v73, v73
	v_exp_f32_e32 v68, v68
	v_exp_f32_e32 v69, v69
	v_add_f32_e32 v70, 1.0, v70
	v_add_f32_e32 v86, 1.0, v66
	v_add_f32_e32 v71, 1.0, v71
	v_add_f32_e32 v87, 1.0, v67
	v_add_f32_e32 v72, 1.0, v72
	v_add_f32_e32 v73, 1.0, v73
	v_add_f32_e32 v88, 1.0, v68
	v_add_f32_e32 v89, 1.0, v69
	v_rcp_f32_e32 v66, v70
	v_rcp_f32_e32 v68, v86
	v_rcp_f32_e32 v67, v71
	v_rcp_f32_e32 v69, v87
	v_rcp_f32_e32 v72, v72
	v_rcp_f32_e32 v73, v73
	v_rcp_f32_e32 v86, v88
	v_rcp_f32_e32 v87, v89
	v_add_u32_e32 v82, 0x80, v150
	v_ashrrev_i32_e32 v83, 31, v82
	v_lshlrev_b64 v[84:85], 6, v[82:83]
	v_lshl_add_u64 v[84:85], s[12:13], 0, v[84:85]
	s_waitcnt vmcnt(2)
; #define GAS __attribute__((address_space(1)))
; __device__ __forceinline__ float sigmoidf_(float x) { return __builtin_amdgcn_rcpf(1.0f + __builtin_amdgcn_exp2f(-1.4426950408889634f * x)); }
; __device__ __forceinline__ void unpack8(v4u w, float (&f)[8]) { f[0] = bflo(w.x); f[1] = bfhi(w.x); f[2] = bflo(w.y); f[3] = bfhi(w.y); f[4] = bflo(w.z); f[5] = bfhi(w.z); f[6] = bflo(w.w); f[7] = bfhi(w.w); }
; __device__ __forceinline__ float row_rs(const float* SS, int row) {
;     const f32x4 a = *(const GAS f32x4*)(SS + (size_t)row * 16), b = *(const GAS f32x4*)(SS + (size_t)row * 16 + 4), c = *(const GAS f32x4*)(SS + (size_t)row * 16 + 8), d = *(const GAS f32x4*)(SS + (size_t)row * 16 + 12);
;     const float s = ((a[0] + a[1]) + (a[2] + a[3])) + ((b[0] + b[1]) + (b[2] + b[3])) + ((c[0] + c[1]) + (c[2] + c[3])) + ((d[0] + d[1]) + (d[2] + d[3]));
;     return __builtin_amdgcn_rsqf(s * (1.f / D) + EPS);
;     __device__ __forceinline__ void operator()(const pg8::f32x4 (&acc)[2][2][4][2], const pg8::Unit& u, int wr, int wc, int fr, int fq) const {
;         const int row0 = u.pm * 256 + wr * 64 + fr, col0 = u.pn * 256 + wc * 32 + 8 * fq;
; #pragma unroll
;         for (int ai = 0; ai < 2; ++ai)
; #pragma unroll
;             for (int m = 0; m < 4; ++m) { if (u.q >= 0 && m != u.q) continue; const int row = row0 + ai * 128 + m * 16; const float rs = row_rs(SS, row);
; #pragma unroll
;                 for (int bj = 0; bj < 2; ++bj) { const int col = col0 + bj * 128; const size_t o = (size_t)row * D + col;
;                     float pw[8], xw[8]; unpack8(*(const GAS v4u*)(PPB + o), pw); unpack8(*(const GAS v4u*)(X2B + o), xw);
;                     const f32x4 a = acc[ai][bj][m][0] * rs, b = acc[ai][bj][m][1] * rs; f32x4 y0, y1;
; #pragma unroll
;                     for (int i = 0; i < 4; ++i) { y0[i] = xw[i] + sigmoidf_(a[i]) * pw[i]; y1[i] = xw[4 + i] + sigmoidf_(b[i]) * pw[4 + i]; }
;                     *(GAS f32x4*)(Y + o) = y0; *(GAS f32x4*)(Y + o + 4) = y1; } }
	v_lshlrev_b32_e32 v70, 16, v190
	v_and_b32_e32 v71, 0xffff0000, v190
	v_lshlrev_b32_e32 v90, 16, v192
	v_lshlrev_b32_e32 v88, 16, v194
	v_and_b32_e32 v89, 0xffff0000, v194
	v_and_b32_e32 v91, 0xffff0000, v192
	v_lshlrev_b32_e32 v92, 16, v196
	v_and_b32_e32 v93, 0xffff0000, v196
	v_lshlrev_b32_e32 v74, 16, v191
	v_and_b32_e32 v75, 0xffff0000, v191
	v_lshlrev_b32_e32 v78, 16, v195
	v_and_b32_e32 v79, 0xffff0000, v195
	v_lshlrev_b32_e32 v76, 16, v193
	v_and_b32_e32 v77, 0xffff0000, v193
	v_lshlrev_b32_e32 v80, 16, v197
	v_and_b32_e32 v81, 0xffff0000, v197
	v_pk_fma_f32 v[66:67], v[66:67], v[70:71], v[88:89]
	v_pk_fma_f32 v[70:71], v[68:69], v[90:91], v[92:93]
	v_pk_fma_f32 v[68:69], v[72:73], v[74:75], v[78:79]
	v_pk_fma_f32 v[72:73], v[86:87], v[76:77], v[80:81]
	global_store_dwordx4 v[108:109], v[66:69], off offset:512
	global_store_dwordx4 v[108:109], v[70:73], off offset:528
	global_load_dwordx4 v[66:69], v[84:85], off
	s_nop 0
	global_load_dwordx4 v[70:73], v[84:85], off offset:16
	global_load_dwordx4 v[74:77], v[84:85], off offset:48
	global_load_dwordx4 v[78:81], v[84:85], off offset:32
	v_lshlrev_b64 v[90:91], 10, v[82:83]
	v_lshl_add_u64 v[92:93], v[90:91], 0, v[146:147]
	v_lshlrev_b64 v[86:87], 1, v[92:93]
	v_lshl_add_u64 v[82:83], s[14:15], 0, v[86:87]
	v_lshl_add_u64 v[86:87], s[10:11], 0, v[86:87]
	global_load_dwordx4 v[82:85], v[82:83], off
	v_lshl_add_u64 v[90:91], v[90:91], 0, v[148:149]
	global_load_dwordx4 v[86:89], v[86:87], off
	v_lshl_add_u64 v[92:93], v[92:93], 2, s[30:31]
	v_lshlrev_b64 v[90:91], 1, v[90:91]
	v_lshl_add_u64 v[94:95], s[14:15], 0, v[90:91]
	v_lshl_add_u64 v[198:199], s[10:11], 0, v[90:91]
	global_load_dwordx4 v[190:193], v[94:95], off
	global_load_dwordx4 v[194:197], v[198:199], off
	s_waitcnt vmcnt(0)
	v_mov_b32_e32 v96, v67
	v_mov_b32_e32 v97, v68
	v_mov_b32_e32 v67, v69
	v_mov_b32_e32 v68, v71
	v_mov_b32_e32 v69, v72
	v_mov_b32_e32 v71, v73
	v_pk_add_f32 v[66:67], v[96:97], v[66:67]
	v_pk_add_f32 v[68:69], v[68:69], v[70:71]
	v_pk_add_f32 v[66:67], v[66:67], v[66:67] op_sel:[0,1] op_sel_hi:[1,0]
	v_pk_add_f32 v[68:69], v[68:69], v[68:69] op_sel:[0,1] op_sel_hi:[1,0]
	v_add_f32_e32 v72, v78, v79
	v_add_f32_e32 v78, v80, v81
	v_mov_b32_e32 v73, v76
	v_mov_b32_e32 v79, v77
	v_mov_b32_e32 v67, v74
	v_mov_b32_e32 v69, v75
	v_pk_add_f32 v[70:71], v[72:73], v[78:79]
	v_pk_add_f32 v[66:67], v[66:67], v[68:69]
	v_lshlrev_b32_e32 v76, 16, v82
	v_pk_add_f32 v[66:67], v[66:67], v[70:71]
	v_and_b32_e32 v77, 0xffff0000, v82
	v_add_f32_e32 v66, v66, v67
	v_fmamk_f32 v66, v66, 0x3a800000, v157
	v_rsq_f32_e32 v70, v66
	v_lshlrev_b32_e32 v80, 16, v86
	v_and_b32_e32 v81, 0xffff0000, v86
	v_lshlrev_b32_e32 v98, 16, v84
	v_mul_f32_e32 v62, v62, v70
	v_mul_f32_e32 v58, v58, v70
	v_mul_f32_e32 v63, v63, v70
	v_mul_f32_e32 v59, v59, v70
	v_mul_f32_e32 v64, v64, v70
	v_mul_f32_e32 v65, v65, v70
	v_mul_f32_e32 v60, v60, v70
	v_mul_f32_e32 v61, v61, v70
	v_mul_f32_e32 v62, 0xbfb8aa3b, v62
	v_mul_f32_e32 v58, 0xbfb8aa3b, v58
	v_mul_f32_e32 v63, 0xbfb8aa3b, v63
	v_mul_f32_e32 v59, 0xbfb8aa3b, v59
	v_mul_f32_e32 v64, 0xbfb8aa3b, v64
	v_mul_f32_e32 v65, 0xbfb8aa3b, v65
	v_mul_f32_e32 v60, 0xbfb8aa3b, v60
	v_mul_f32_e32 v61, 0xbfb8aa3b, v61
	v_exp_f32_e32 v62, v62
	v_exp_f32_e32 v58, v58
	v_exp_f32_e32 v63, v63
	v_exp_f32_e32 v59, v59
	v_exp_f32_e32 v64, v64
	v_exp_f32_e32 v65, v65
	v_exp_f32_e32 v60, v60
	v_exp_f32_e32 v61, v61
	v_add_f32_e32 v62, 1.0, v62
	v_add_f32_e32 v68, 1.0, v58
	v_add_f32_e32 v63, 1.0, v63
	v_add_f32_e32 v69, 1.0, v59
	v_add_f32_e32 v64, 1.0, v64
	v_add_f32_e32 v65, 1.0, v65
	v_add_f32_e32 v71, 1.0, v60
	v_add_f32_e32 v72, 1.0, v61
	v_rcp_f32_e32 v58, v62
	v_rcp_f32_e32 v60, v68
	v_rcp_f32_e32 v59, v63
	v_rcp_f32_e32 v61, v69
	v_rcp_f32_e32 v64, v64
	v_rcp_f32_e32 v65, v65
	v_rcp_f32_e32 v68, v71
	v_rcp_f32_e32 v69, v72
	v_and_b32_e32 v99, 0xffff0000, v84
	v_lshlrev_b32_e32 v100, 16, v88
	v_and_b32_e32 v101, 0xffff0000, v88
	v_lshlrev_b32_e32 v82, 16, v83
	v_and_b32_e32 v83, 0xffff0000, v83
	v_lshlrev_b32_e32 v86, 16, v87
	v_and_b32_e32 v87, 0xffff0000, v87
	v_lshlrev_b32_e32 v84, 16, v85
	v_and_b32_e32 v85, 0xffff0000, v85
	v_lshlrev_b32_e32 v66, 16, v89
	v_and_b32_e32 v67, 0xffff0000, v89
	v_pk_fma_f32 v[58:59], v[58:59], v[76:77], v[80:81]
	v_pk_fma_f32 v[62:63], v[60:61], v[98:99], v[100:101]
	v_pk_fma_f32 v[60:61], v[64:65], v[82:83], v[86:87]
	v_pk_fma_f32 v[64:65], v[68:69], v[84:85], v[66:67]
	global_store_dwordx4 v[92:93], v[58:61], off
	global_store_dwordx4 v[92:93], v[62:65], off offset:16
	v_mul_f32_e32 v54, v54, v70
	v_mul_f32_e32 v50, v50, v70
	v_mul_f32_e32 v55, v55, v70
	v_mul_f32_e32 v51, v51, v70
	v_mul_f32_e32 v56, v56, v70
	v_mul_f32_e32 v57, v57, v70
	v_mul_f32_e32 v52, v52, v70
	v_mul_f32_e32 v53, v53, v70
	v_mul_f32_e32 v54, 0xbfb8aa3b, v54
	v_mul_f32_e32 v50, 0xbfb8aa3b, v50
	v_mul_f32_e32 v55, 0xbfb8aa3b, v55
	v_mul_f32_e32 v51, 0xbfb8aa3b, v51
	v_mul_f32_e32 v56, 0xbfb8aa3b, v56
	v_mul_f32_e32 v57, 0xbfb8aa3b, v57
	v_mul_f32_e32 v52, 0xbfb8aa3b, v52
	v_mul_f32_e32 v53, 0xbfb8aa3b, v53
	v_exp_f32_e32 v54, v54
	v_exp_f32_e32 v50, v50
	v_exp_f32_e32 v55, v55
	v_exp_f32_e32 v51, v51
	v_exp_f32_e32 v56, v56
	v_exp_f32_e32 v57, v57
	v_exp_f32_e32 v52, v52
	v_exp_f32_e32 v53, v53
	v_add_f32_e32 v54, 1.0, v54
	v_add_f32_e32 v70, 1.0, v50
	v_add_f32_e32 v55, 1.0, v55
	v_add_f32_e32 v71, 1.0, v51
	v_add_f32_e32 v56, 1.0, v56
	v_add_f32_e32 v57, 1.0, v57
	v_add_f32_e32 v72, 1.0, v52
	v_add_f32_e32 v73, 1.0, v53
	v_rcp_f32_e32 v50, v54
	v_rcp_f32_e32 v52, v70
	v_rcp_f32_e32 v51, v55
	v_rcp_f32_e32 v53, v71
	v_rcp_f32_e32 v56, v56
	v_rcp_f32_e32 v57, v57
	v_rcp_f32_e32 v70, v72
	v_rcp_f32_e32 v71, v73
	v_add_u32_e32 v66, 0x90, v150
	v_ashrrev_i32_e32 v67, 31, v66
	v_lshlrev_b64 v[68:69], 6, v[66:67]
	v_lshl_add_u64 v[68:69], s[12:13], 0, v[68:69]
	s_waitcnt vmcnt(2)
; #define GAS __attribute__((address_space(1)))
; __device__ __forceinline__ float sigmoidf_(float x) { return __builtin_amdgcn_rcpf(1.0f + __builtin_amdgcn_exp2f(-1.4426950408889634f * x)); }
; __device__ __forceinline__ void unpack8(v4u w, float (&f)[8]) { f[0] = bflo(w.x); f[1] = bfhi(w.x); f[2] = bflo(w.y); f[3] = bfhi(w.y); f[4] = bflo(w.z); f[5] = bfhi(w.z); f[6] = bflo(w.w); f[7] = bfhi(w.w); }
; __device__ __forceinline__ float row_rs(const float* SS, int row) {
;     const f32x4 a = *(const GAS f32x4*)(SS + (size_t)row * 16), b = *(const GAS f32x4*)(SS + (size_t)row * 16 + 4), c = *(const GAS f32x4*)(SS + (size_t)row * 16 + 8), d = *(const GAS f32x4*)(SS + (size_t)row * 16 + 12);
;     const float s = ((a[0] + a[1]) + (a[2] + a[3])) + ((b[0] + b[1]) + (b[2] + b[3])) + ((c[0] + c[1]) + (c[2] + c[3])) + ((d[0] + d[1]) + (d[2] + d[3]));
;     return __builtin_amdgcn_rsqf(s * (1.f / D) + EPS);
;     __device__ __forceinline__ void operator()(const pg8::f32x4 (&acc)[2][2][4][2], const pg8::Unit& u, int wr, int wc, int fr, int fq) const {
;         const int row0 = u.pm * 256 + wr * 64 + fr, col0 = u.pn * 256 + wc * 32 + 8 * fq;
; #pragma unroll
;         for (int ai = 0; ai < 2; ++ai)
; #pragma unroll
;             for (int m = 0; m < 4; ++m) { if (u.q >= 0 && m != u.q) continue; const int row = row0 + ai * 128 + m * 16; const float rs = row_rs(SS, row);
; #pragma unroll
;                 for (int bj = 0; bj < 2; ++bj) { const int col = col0 + bj * 128; const size_t o = (size_t)row * D + col;
;                     float pw[8], xw[8]; unpack8(*(const GAS v4u*)(PPB + o), pw); unpack8(*(const GAS v4u*)(X2B + o), xw);
;                     const f32x4 a = acc[ai][bj][m][0] * rs, b = acc[ai][bj][m][1] * rs; f32x4 y0, y1;
; #pragma unroll
;                     for (int i = 0; i < 4; ++i) { y0[i] = xw[i] + sigmoidf_(a[i]) * pw[i]; y1[i] = xw[4 + i] + sigmoidf_(b[i]) * pw[4 + i]; }
;                     *(GAS f32x4*)(Y + o) = y0; *(GAS f32x4*)(Y + o + 4) = y1; } }
	v_lshlrev_b32_e32 v54, 16, v190
	v_and_b32_e32 v55, 0xffff0000, v190
	v_lshlrev_b32_e32 v74, 16, v192
	v_lshlrev_b32_e32 v72, 16, v194
	v_and_b32_e32 v73, 0xffff0000, v194
	v_and_b32_e32 v75, 0xffff0000, v192
	v_lshlrev_b32_e32 v76, 16, v196
	v_and_b32_e32 v77, 0xffff0000, v196
	v_lshlrev_b32_e32 v58, 16, v191
	v_and_b32_e32 v59, 0xffff0000, v191
	v_lshlrev_b32_e32 v62, 16, v195
	v_and_b32_e32 v63, 0xffff0000, v195
	v_lshlrev_b32_e32 v60, 16, v193
	v_and_b32_e32 v61, 0xffff0000, v193
	v_lshlrev_b32_e32 v64, 16, v197
	v_and_b32_e32 v65, 0xffff0000, v197
	v_pk_fma_f32 v[50:51], v[50:51], v[54:55], v[72:73]
	v_pk_fma_f32 v[54:55], v[52:53], v[74:75], v[76:77]
	v_pk_fma_f32 v[52:53], v[56:57], v[58:59], v[62:63]
	v_pk_fma_f32 v[56:57], v[70:71], v[60:61], v[64:65]
	global_store_dwordx4 v[92:93], v[50:53], off offset:512
	global_store_dwordx4 v[92:93], v[54:57], off offset:528
	global_load_dwordx4 v[50:53], v[68:69], off
	s_nop 0
	global_load_dwordx4 v[54:57], v[68:69], off offset:16
	global_load_dwordx4 v[58:61], v[68:69], off offset:48
	global_load_dwordx4 v[62:65], v[68:69], off offset:32
	v_lshlrev_b64 v[74:75], 10, v[66:67]
	v_lshl_add_u64 v[76:77], v[74:75], 0, v[146:147]
	v_lshlrev_b64 v[70:71], 1, v[76:77]
	v_lshl_add_u64 v[66:67], s[14:15], 0, v[70:71]
	v_lshl_add_u64 v[70:71], s[10:11], 0, v[70:71]
	global_load_dwordx4 v[66:69], v[66:67], off
	v_lshl_add_u64 v[74:75], v[74:75], 0, v[148:149]
	global_load_dwordx4 v[70:73], v[70:71], off
	v_lshl_add_u64 v[76:77], v[76:77], 2, s[30:31]
	v_lshlrev_b64 v[74:75], 1, v[74:75]
	v_lshl_add_u64 v[78:79], s[14:15], 0, v[74:75]
	v_lshl_add_u64 v[198:199], s[10:11], 0, v[74:75]
	global_load_dwordx4 v[190:193], v[78:79], off
	global_load_dwordx4 v[194:197], v[198:199], off
	s_waitcnt vmcnt(0)
	v_mov_b32_e32 v80, v51
	v_mov_b32_e32 v81, v52
	v_mov_b32_e32 v51, v53
	v_mov_b32_e32 v52, v55
	v_mov_b32_e32 v53, v56
	v_mov_b32_e32 v55, v57
	v_pk_add_f32 v[50:51], v[80:81], v[50:51]
	v_pk_add_f32 v[52:53], v[52:53], v[54:55]
	v_pk_add_f32 v[50:51], v[50:51], v[50:51] op_sel:[0,1] op_sel_hi:[1,0]
	v_pk_add_f32 v[52:53], v[52:53], v[52:53] op_sel:[0,1] op_sel_hi:[1,0]
	v_add_f32_e32 v56, v62, v63
	v_add_f32_e32 v62, v64, v65
	v_mov_b32_e32 v57, v60
	v_mov_b32_e32 v63, v61
	v_mov_b32_e32 v51, v58
	v_mov_b32_e32 v53, v59
	v_pk_add_f32 v[54:55], v[56:57], v[62:63]
	v_pk_add_f32 v[50:51], v[50:51], v[52:53]
	v_lshlrev_b32_e32 v60, 16, v66
	v_pk_add_f32 v[50:51], v[50:51], v[54:55]
	v_and_b32_e32 v61, 0xffff0000, v66
	v_add_f32_e32 v50, v50, v51
	v_fmamk_f32 v50, v50, 0x3a800000, v157
	v_rsq_f32_e32 v54, v50
	v_lshlrev_b32_e32 v64, 16, v70
	v_and_b32_e32 v65, 0xffff0000, v70
	v_lshlrev_b32_e32 v82, 16, v68
	v_mul_f32_e32 v46, v46, v54
	v_mul_f32_e32 v42, v42, v54
	v_mul_f32_e32 v47, v47, v54
	v_mul_f32_e32 v43, v43, v54
	v_mul_f32_e32 v48, v48, v54
	v_mul_f32_e32 v49, v49, v54
	v_mul_f32_e32 v44, v44, v54
	v_mul_f32_e32 v45, v45, v54
	v_mul_f32_e32 v46, 0xbfb8aa3b, v46
	v_mul_f32_e32 v42, 0xbfb8aa3b, v42
	v_mul_f32_e32 v47, 0xbfb8aa3b, v47
	v_mul_f32_e32 v43, 0xbfb8aa3b, v43
	v_mul_f32_e32 v48, 0xbfb8aa3b, v48
	v_mul_f32_e32 v49, 0xbfb8aa3b, v49
	v_mul_f32_e32 v44, 0xbfb8aa3b, v44
	v_mul_f32_e32 v45, 0xbfb8aa3b, v45
	v_exp_f32_e32 v46, v46
	v_exp_f32_e32 v42, v42
	v_exp_f32_e32 v47, v47
	v_exp_f32_e32 v43, v43
	v_exp_f32_e32 v48, v48
	v_exp_f32_e32 v49, v49
	v_exp_f32_e32 v44, v44
	v_exp_f32_e32 v45, v45
	v_add_f32_e32 v46, 1.0, v46
	v_add_f32_e32 v52, 1.0, v42
	v_add_f32_e32 v47, 1.0, v47
	v_add_f32_e32 v53, 1.0, v43
	v_add_f32_e32 v48, 1.0, v48
	v_add_f32_e32 v49, 1.0, v49
	v_add_f32_e32 v55, 1.0, v44
	v_add_f32_e32 v56, 1.0, v45
	v_rcp_f32_e32 v42, v46
	v_rcp_f32_e32 v44, v52
	v_rcp_f32_e32 v43, v47
	v_rcp_f32_e32 v45, v53
	v_rcp_f32_e32 v48, v48
	v_rcp_f32_e32 v49, v49
	v_rcp_f32_e32 v52, v55
	v_rcp_f32_e32 v53, v56
	v_and_b32_e32 v83, 0xffff0000, v68
	v_lshlrev_b32_e32 v84, 16, v72
	v_and_b32_e32 v85, 0xffff0000, v72
	v_lshlrev_b32_e32 v66, 16, v67
	v_and_b32_e32 v67, 0xffff0000, v67
	v_lshlrev_b32_e32 v70, 16, v71
	v_and_b32_e32 v71, 0xffff0000, v71
	v_lshlrev_b32_e32 v68, 16, v69
	v_and_b32_e32 v69, 0xffff0000, v69
	v_lshlrev_b32_e32 v50, 16, v73
	v_and_b32_e32 v51, 0xffff0000, v73
	v_pk_fma_f32 v[42:43], v[42:43], v[60:61], v[64:65]
	v_pk_fma_f32 v[46:47], v[44:45], v[82:83], v[84:85]
	v_pk_fma_f32 v[44:45], v[48:49], v[66:67], v[70:71]
	v_pk_fma_f32 v[48:49], v[52:53], v[68:69], v[50:51]
	global_store_dwordx4 v[76:77], v[42:45], off
	global_store_dwordx4 v[76:77], v[46:49], off offset:16
	v_mul_f32_e32 v38, v38, v54
	v_mul_f32_e32 v34, v34, v54
	v_mul_f32_e32 v39, v39, v54
	v_mul_f32_e32 v35, v35, v54
	v_mul_f32_e32 v40, v40, v54
	v_mul_f32_e32 v41, v41, v54
	v_mul_f32_e32 v36, v36, v54
	v_mul_f32_e32 v37, v37, v54
	v_mul_f32_e32 v38, 0xbfb8aa3b, v38
	v_mul_f32_e32 v34, 0xbfb8aa3b, v34
	v_mul_f32_e32 v39, 0xbfb8aa3b, v39
	v_mul_f32_e32 v35, 0xbfb8aa3b, v35
	v_mul_f32_e32 v40, 0xbfb8aa3b, v40
	v_mul_f32_e32 v41, 0xbfb8aa3b, v41
	v_mul_f32_e32 v36, 0xbfb8aa3b, v36
	v_mul_f32_e32 v37, 0xbfb8aa3b, v37
	v_exp_f32_e32 v38, v38
	v_exp_f32_e32 v34, v34
	v_exp_f32_e32 v39, v39
	v_exp_f32_e32 v35, v35
	v_exp_f32_e32 v40, v40
	v_exp_f32_e32 v41, v41
	v_exp_f32_e32 v36, v36
	v_exp_f32_e32 v37, v37
	v_add_f32_e32 v38, 1.0, v38
	v_add_f32_e32 v54, 1.0, v34
	v_add_f32_e32 v39, 1.0, v39
	v_add_f32_e32 v55, 1.0, v35
	v_add_f32_e32 v40, 1.0, v40
	v_add_f32_e32 v41, 1.0, v41
	v_add_f32_e32 v56, 1.0, v36
	v_add_f32_e32 v57, 1.0, v37
	v_rcp_f32_e32 v34, v38
	v_rcp_f32_e32 v36, v54
	v_rcp_f32_e32 v35, v39
	v_rcp_f32_e32 v37, v55
	v_rcp_f32_e32 v40, v40
	v_rcp_f32_e32 v41, v41
	v_rcp_f32_e32 v54, v56
	v_rcp_f32_e32 v55, v57
	v_add_u32_e32 v50, 0xa0, v150
	v_ashrrev_i32_e32 v51, 31, v50
	v_lshlrev_b64 v[52:53], 6, v[50:51]
	v_lshl_add_u64 v[52:53], s[12:13], 0, v[52:53]
	s_waitcnt vmcnt(2)
; #define GAS __attribute__((address_space(1)))
; __device__ __forceinline__ float sigmoidf_(float x) { return __builtin_amdgcn_rcpf(1.0f + __builtin_amdgcn_exp2f(-1.4426950408889634f * x)); }
; __device__ __forceinline__ void unpack8(v4u w, float (&f)[8]) { f[0] = bflo(w.x); f[1] = bfhi(w.x); f[2] = bflo(w.y); f[3] = bfhi(w.y); f[4] = bflo(w.z); f[5] = bfhi(w.z); f[6] = bflo(w.w); f[7] = bfhi(w.w); }
; __device__ __forceinline__ float row_rs(const float* SS, int row) {
;     const f32x4 a = *(const GAS f32x4*)(SS + (size_t)row * 16), b = *(const GAS f32x4*)(SS + (size_t)row * 16 + 4), c = *(const GAS f32x4*)(SS + (size_t)row * 16 + 8), d = *(const GAS f32x4*)(SS + (size_t)row * 16 + 12);
;     const float s = ((a[0] + a[1]) + (a[2] + a[3])) + ((b[0] + b[1]) + (b[2] + b[3])) + ((c[0] + c[1]) + (c[2] + c[3])) + ((d[0] + d[1]) + (d[2] + d[3]));
;     return __builtin_amdgcn_rsqf(s * (1.f / D) + EPS);
;     __device__ __forceinline__ void operator()(const pg8::f32x4 (&acc)[2][2][4][2], const pg8::Unit& u, int wr, int wc, int fr, int fq) const {
;         const int row0 = u.pm * 256 + wr * 64 + fr, col0 = u.pn * 256 + wc * 32 + 8 * fq;
; #pragma unroll
;         for (int ai = 0; ai < 2; ++ai)
; #pragma unroll
;             for (int m = 0; m < 4; ++m) { if (u.q >= 0 && m != u.q) continue; const int row = row0 + ai * 128 + m * 16; const float rs = row_rs(SS, row);
; #pragma unroll
;                 for (int bj = 0; bj < 2; ++bj) { const int col = col0 + bj * 128; const size_t o = (size_t)row * D + col;
;                     float pw[8], xw[8]; unpack8(*(const GAS v4u*)(PPB + o), pw); unpack8(*(const GAS v4u*)(X2B + o), xw);
;                     const f32x4 a = acc[ai][bj][m][0] * rs, b = acc[ai][bj][m][1] * rs; f32x4 y0, y1;
; #pragma unroll
;                     for (int i = 0; i < 4; ++i) { y0[i] = xw[i] + sigmoidf_(a[i]) * pw[i]; y1[i] = xw[4 + i] + sigmoidf_(b[i]) * pw[4 + i]; }
;                     *(GAS f32x4*)(Y + o) = y0; *(GAS f32x4*)(Y + o + 4) = y1; } }
	v_lshlrev_b32_e32 v38, 16, v190
	v_and_b32_e32 v39, 0xffff0000, v190
	v_lshlrev_b32_e32 v58, 16, v192
	v_lshlrev_b32_e32 v56, 16, v194
	v_and_b32_e32 v57, 0xffff0000, v194
	v_and_b32_e32 v59, 0xffff0000, v192
	v_lshlrev_b32_e32 v60, 16, v196
	v_and_b32_e32 v61, 0xffff0000, v196
	v_lshlrev_b32_e32 v42, 16, v191
	v_and_b32_e32 v43, 0xffff0000, v191
	v_lshlrev_b32_e32 v46, 16, v195
	v_and_b32_e32 v47, 0xffff0000, v195
	v_lshlrev_b32_e32 v44, 16, v193
	v_and_b32_e32 v45, 0xffff0000, v193
	v_lshlrev_b32_e32 v48, 16, v197
	v_and_b32_e32 v49, 0xffff0000, v197
	v_pk_fma_f32 v[34:35], v[34:35], v[38:39], v[56:57]
	v_pk_fma_f32 v[38:39], v[36:37], v[58:59], v[60:61]
	v_pk_fma_f32 v[36:37], v[40:41], v[42:43], v[46:47]
	v_pk_fma_f32 v[40:41], v[54:55], v[44:45], v[48:49]
	global_store_dwordx4 v[76:77], v[34:37], off offset:512
	global_store_dwordx4 v[76:77], v[38:41], off offset:528
	global_load_dwordx4 v[34:37], v[52:53], off
	s_nop 0
	global_load_dwordx4 v[38:41], v[52:53], off offset:16
	global_load_dwordx4 v[42:45], v[52:53], off offset:48
	global_load_dwordx4 v[46:49], v[52:53], off offset:32
	v_lshlrev_b64 v[58:59], 10, v[50:51]
	v_lshl_add_u64 v[60:61], v[58:59], 0, v[146:147]
	v_lshlrev_b64 v[54:55], 1, v[60:61]
	v_lshl_add_u64 v[50:51], s[14:15], 0, v[54:55]
	v_lshl_add_u64 v[54:55], s[10:11], 0, v[54:55]
	global_load_dwordx4 v[50:53], v[50:51], off
	v_lshl_add_u64 v[58:59], v[58:59], 0, v[148:149]
	global_load_dwordx4 v[54:57], v[54:55], off
	v_lshl_add_u64 v[60:61], v[60:61], 2, s[30:31]
	v_lshlrev_b64 v[58:59], 1, v[58:59]
	v_lshl_add_u64 v[62:63], s[14:15], 0, v[58:59]
	v_lshl_add_u64 v[198:199], s[10:11], 0, v[58:59]
	global_load_dwordx4 v[190:193], v[62:63], off
	global_load_dwordx4 v[194:197], v[198:199], off
	s_waitcnt vmcnt(0)
	v_mov_b32_e32 v64, v35
	v_mov_b32_e32 v65, v36
	v_mov_b32_e32 v35, v37
	v_mov_b32_e32 v36, v39
	v_mov_b32_e32 v37, v40
	v_mov_b32_e32 v39, v41
	v_pk_add_f32 v[34:35], v[64:65], v[34:35]
	v_pk_add_f32 v[36:37], v[36:37], v[38:39]
	v_pk_add_f32 v[34:35], v[34:35], v[34:35] op_sel:[0,1] op_sel_hi:[1,0]
	v_pk_add_f32 v[36:37], v[36:37], v[36:37] op_sel:[0,1] op_sel_hi:[1,0]
	v_add_f32_e32 v40, v46, v47
	v_add_f32_e32 v46, v48, v49
	v_mov_b32_e32 v41, v44
	v_mov_b32_e32 v47, v45
	v_mov_b32_e32 v35, v42
	v_mov_b32_e32 v37, v43
	v_pk_add_f32 v[38:39], v[40:41], v[46:47]
	v_pk_add_f32 v[34:35], v[34:35], v[36:37]
	v_lshlrev_b32_e32 v44, 16, v50
	v_pk_add_f32 v[34:35], v[34:35], v[38:39]
	v_and_b32_e32 v45, 0xffff0000, v50
	v_add_f32_e32 v34, v34, v35
	v_fmamk_f32 v34, v34, 0x3a800000, v157
	v_rsq_f32_e32 v38, v34
	v_lshlrev_b32_e32 v48, 16, v54
	v_and_b32_e32 v49, 0xffff0000, v54
	v_lshlrev_b32_e32 v66, 16, v52
	v_mul_f32_e32 v30, v30, v38
	v_mul_f32_e32 v26, v26, v38
	v_mul_f32_e32 v31, v31, v38
	v_mul_f32_e32 v27, v27, v38
	v_mul_f32_e32 v32, v32, v38
	v_mul_f32_e32 v33, v33, v38
	v_mul_f32_e32 v28, v28, v38
	v_mul_f32_e32 v29, v29, v38
	v_mul_f32_e32 v30, 0xbfb8aa3b, v30
	v_mul_f32_e32 v26, 0xbfb8aa3b, v26
	v_mul_f32_e32 v31, 0xbfb8aa3b, v31
	v_mul_f32_e32 v27, 0xbfb8aa3b, v27
	v_mul_f32_e32 v32, 0xbfb8aa3b, v32
	v_mul_f32_e32 v33, 0xbfb8aa3b, v33
	v_mul_f32_e32 v28, 0xbfb8aa3b, v28
	v_mul_f32_e32 v29, 0xbfb8aa3b, v29
	v_exp_f32_e32 v30, v30
	v_exp_f32_e32 v26, v26
	v_exp_f32_e32 v31, v31
	v_exp_f32_e32 v27, v27
	v_exp_f32_e32 v32, v32
	v_exp_f32_e32 v33, v33
	v_exp_f32_e32 v28, v28
	v_exp_f32_e32 v29, v29
	v_add_f32_e32 v30, 1.0, v30
	v_add_f32_e32 v36, 1.0, v26
	v_add_f32_e32 v31, 1.0, v31
	v_add_f32_e32 v37, 1.0, v27
	v_add_f32_e32 v32, 1.0, v32
	v_add_f32_e32 v33, 1.0, v33
	v_add_f32_e32 v39, 1.0, v28
	v_add_f32_e32 v40, 1.0, v29
	v_rcp_f32_e32 v26, v30
	v_rcp_f32_e32 v28, v36
	v_rcp_f32_e32 v27, v31
	v_rcp_f32_e32 v29, v37
	v_rcp_f32_e32 v32, v32
	v_rcp_f32_e32 v33, v33
	v_rcp_f32_e32 v36, v39
	v_rcp_f32_e32 v37, v40
	v_and_b32_e32 v67, 0xffff0000, v52
	v_lshlrev_b32_e32 v68, 16, v56
	v_and_b32_e32 v69, 0xffff0000, v56
	v_lshlrev_b32_e32 v50, 16, v51
	v_and_b32_e32 v51, 0xffff0000, v51
	v_lshlrev_b32_e32 v54, 16, v55
	v_and_b32_e32 v55, 0xffff0000, v55
	v_lshlrev_b32_e32 v52, 16, v53
	v_and_b32_e32 v53, 0xffff0000, v53
	v_lshlrev_b32_e32 v34, 16, v57
	v_and_b32_e32 v35, 0xffff0000, v57
	v_pk_fma_f32 v[26:27], v[26:27], v[44:45], v[48:49]
	v_pk_fma_f32 v[30:31], v[28:29], v[66:67], v[68:69]
	v_pk_fma_f32 v[28:29], v[32:33], v[50:51], v[54:55]
	v_pk_fma_f32 v[32:33], v[36:37], v[52:53], v[34:35]
	global_store_dwordx4 v[60:61], v[26:29], off
	global_store_dwordx4 v[60:61], v[30:33], off offset:16
	v_mul_f32_e32 v22, v22, v38
	v_mul_f32_e32 v18, v18, v38
	v_mul_f32_e32 v23, v23, v38
	v_mul_f32_e32 v19, v19, v38
	v_mul_f32_e32 v24, v24, v38
	v_mul_f32_e32 v25, v25, v38
	v_mul_f32_e32 v20, v20, v38
	v_mul_f32_e32 v21, v21, v38
	v_mul_f32_e32 v22, 0xbfb8aa3b, v22
	v_mul_f32_e32 v18, 0xbfb8aa3b, v18
	v_mul_f32_e32 v23, 0xbfb8aa3b, v23
	v_mul_f32_e32 v19, 0xbfb8aa3b, v19
	v_mul_f32_e32 v24, 0xbfb8aa3b, v24
	v_mul_f32_e32 v25, 0xbfb8aa3b, v25
	v_mul_f32_e32 v20, 0xbfb8aa3b, v20
	v_mul_f32_e32 v21, 0xbfb8aa3b, v21
	v_exp_f32_e32 v22, v22
	v_exp_f32_e32 v18, v18
	v_exp_f32_e32 v23, v23
	v_exp_f32_e32 v19, v19
	v_exp_f32_e32 v24, v24
	v_exp_f32_e32 v25, v25
	v_exp_f32_e32 v20, v20
	v_exp_f32_e32 v21, v21
	v_add_f32_e32 v22, 1.0, v22
	v_add_f32_e32 v38, 1.0, v18
	v_add_f32_e32 v23, 1.0, v23
	v_add_f32_e32 v39, 1.0, v19
	v_add_f32_e32 v24, 1.0, v24
	v_add_f32_e32 v25, 1.0, v25
	v_add_f32_e32 v40, 1.0, v20
	v_add_f32_e32 v41, 1.0, v21
	v_rcp_f32_e32 v18, v22
	v_rcp_f32_e32 v20, v38
	v_rcp_f32_e32 v19, v23
	v_rcp_f32_e32 v21, v39
	v_rcp_f32_e32 v24, v24
	v_rcp_f32_e32 v25, v25
	v_rcp_f32_e32 v38, v40
	v_rcp_f32_e32 v39, v41
	v_add_u32_e32 v34, 0xb0, v150
	v_ashrrev_i32_e32 v35, 31, v34
	v_lshlrev_b64 v[36:37], 6, v[34:35]
	v_lshl_add_u64 v[36:37], s[12:13], 0, v[36:37]
	s_waitcnt vmcnt(2)
; #define GAS __attribute__((address_space(1)))
; __device__ __forceinline__ float sigmoidf_(float x) { return __builtin_amdgcn_rcpf(1.0f + __builtin_amdgcn_exp2f(-1.4426950408889634f * x)); }
; #define PG8_BAR __builtin_amdgcn_s_barrier()
; __device__ __forceinline__ void unpack8(v4u w, float (&f)[8]) { f[0] = bflo(w.x); f[1] = bfhi(w.x); f[2] = bflo(w.y); f[3] = bfhi(w.y); f[4] = bflo(w.z); f[5] = bfhi(w.z); f[6] = bflo(w.w); f[7] = bfhi(w.w); }
; template <class Epi, bool ALIGN_EPI = true, bool SP2 = true, bool QUARTER = false, class Sched = Order>
; __device__ __forceinline__ void gemm_phase(PG8_LAS unsigned char* lds, const Gemm g, const Sched& S, const Epi& E) {
;     ...
;         if (!has_next) break;
; #pragma unroll
;         for (int a = 0; a < 2; ++a)
; #pragma unroll
;             for (int b = 0; b < 2; ++b)
; #pragma unroll
;                 for (int m = 0; m < 4; ++m)
; #pragma unroll
;                     for (int n = 0; n < 2; ++n) acc[a][b][m][n] = (f32x4){0.f, 0.f, 0.f, 0.f};
;         cur = nxt; cA = nA; cB = nB; ++ui;
;         if constexpr (ALIGN_EPI) { if (wr == 1) PG8_BAR; }
;     __device__ __forceinline__ void operator()(const pg8::f32x4 (&acc)[2][2][4][2], const pg8::Unit& u, int wr, int wc, int fr, int fq) const {
;         const int row0 = u.pm * 256 + wr * 64 + fr, col0 = u.pn * 256 + wc * 32 + 8 * fq;
; #pragma unroll
;         for (int ai = 0; ai < 2; ++ai)
; #pragma unroll
;             for (int m = 0; m < 4; ++m) { if (u.q >= 0 && m != u.q) continue; const int row = row0 + ai * 128 + m * 16; const float rs = row_rs(SS, row);
; #pragma unroll
;                 for (int bj = 0; bj < 2; ++bj) { const int col = col0 + bj * 128; const size_t o = (size_t)row * D + col;
;                     float pw[8], xw[8]; unpack8(*(const GAS v4u*)(PPB + o), pw); unpack8(*(const GAS v4u*)(X2B + o), xw);
;                     const f32x4 a = acc[ai][bj][m][0] * rs, b = acc[ai][bj][m][1] * rs; f32x4 y0, y1;
; #pragma unroll
;                     for (int i = 0; i < 4; ++i) { y0[i] = xw[i] + sigmoidf_(a[i]) * pw[i]; y1[i] = xw[4 + i] + sigmoidf_(b[i]) * pw[4 + i]; }
;                     *(GAS f32x4*)(Y + o) = y0; *(GAS f32x4*)(Y + o + 4) = y1; } }
	v_lshlrev_b32_e32 v22, 16, v190
	v_and_b32_e32 v23, 0xffff0000, v190
	v_lshlrev_b32_e32 v42, 16, v192
	v_lshlrev_b32_e32 v40, 16, v194
	v_and_b32_e32 v41, 0xffff0000, v194
	v_and_b32_e32 v43, 0xffff0000, v192
	v_lshlrev_b32_e32 v44, 16, v196
	v_and_b32_e32 v45, 0xffff0000, v196
	v_lshlrev_b32_e32 v26, 16, v191
	v_and_b32_e32 v27, 0xffff0000, v191
	v_lshlrev_b32_e32 v30, 16, v195
	v_and_b32_e32 v31, 0xffff0000, v195
	v_lshlrev_b32_e32 v28, 16, v193
	v_and_b32_e32 v29, 0xffff0000, v193
	v_lshlrev_b32_e32 v32, 16, v197
	v_and_b32_e32 v33, 0xffff0000, v197
	v_pk_fma_f32 v[18:19], v[18:19], v[22:23], v[40:41]
	v_pk_fma_f32 v[22:23], v[20:21], v[42:43], v[44:45]
	v_pk_fma_f32 v[20:21], v[24:25], v[26:27], v[30:31]
	v_pk_fma_f32 v[24:25], v[38:39], v[28:29], v[32:33]
	global_store_dwordx4 v[60:61], v[18:21], off offset:512
	global_store_dwordx4 v[60:61], v[22:25], off offset:528
	global_load_dwordx4 v[18:21], v[36:37], off
	s_nop 0
	global_load_dwordx4 v[22:25], v[36:37], off offset:16
	global_load_dwordx4 v[26:29], v[36:37], off offset:48
	global_load_dwordx4 v[30:33], v[36:37], off offset:32
	v_lshlrev_b64 v[42:43], 10, v[34:35]
	v_lshl_add_u64 v[44:45], v[42:43], 0, v[146:147]
	v_lshlrev_b64 v[38:39], 1, v[44:45]
	v_lshl_add_u64 v[34:35], s[14:15], 0, v[38:39]
	v_lshl_add_u64 v[38:39], s[10:11], 0, v[38:39]
	global_load_dwordx4 v[34:37], v[34:35], off
	v_lshl_add_u64 v[42:43], v[42:43], 0, v[148:149]
	global_load_dwordx4 v[38:41], v[38:39], off
	v_lshl_add_u64 v[44:45], v[44:45], 2, s[30:31]
	v_lshlrev_b64 v[42:43], 1, v[42:43]
	v_lshl_add_u64 v[46:47], s[14:15], 0, v[42:43]
	v_lshl_add_u64 v[198:199], s[10:11], 0, v[42:43]
	global_load_dwordx4 v[190:193], v[46:47], off
	global_load_dwordx4 v[194:197], v[198:199], off
	s_waitcnt vmcnt(0)
	v_mov_b32_e32 v48, v19
	v_mov_b32_e32 v49, v20
	v_mov_b32_e32 v19, v21
	v_mov_b32_e32 v20, v23
	v_mov_b32_e32 v21, v24
	v_mov_b32_e32 v23, v25
	v_pk_add_f32 v[18:19], v[48:49], v[18:19]
	v_pk_add_f32 v[20:21], v[20:21], v[22:23]
	v_pk_add_f32 v[18:19], v[18:19], v[18:19] op_sel:[0,1] op_sel_hi:[1,0]
	v_pk_add_f32 v[20:21], v[20:21], v[20:21] op_sel:[0,1] op_sel_hi:[1,0]
	v_add_f32_e32 v24, v30, v31
	v_add_f32_e32 v30, v32, v33
	v_mov_b32_e32 v25, v28
	v_mov_b32_e32 v31, v29
	v_mov_b32_e32 v19, v26
	v_mov_b32_e32 v21, v27
	v_pk_add_f32 v[22:23], v[24:25], v[30:31]
	v_pk_add_f32 v[18:19], v[18:19], v[20:21]
	v_lshlrev_b32_e32 v28, 16, v34
	v_pk_add_f32 v[18:19], v[18:19], v[22:23]
	v_and_b32_e32 v29, 0xffff0000, v34
	v_add_f32_e32 v18, v18, v19
	v_fmamk_f32 v18, v18, 0x3a800000, v157
	v_rsq_f32_e32 v22, v18
	v_lshlrev_b32_e32 v32, 16, v38
	v_and_b32_e32 v33, 0xffff0000, v38
	v_lshlrev_b32_e32 v50, 16, v36
	v_mul_f32_e32 v14, v14, v22
	v_mul_f32_e32 v10, v10, v22
	v_mul_f32_e32 v15, v15, v22
	v_mul_f32_e32 v11, v11, v22
	v_mul_f32_e32 v16, v16, v22
	v_mul_f32_e32 v17, v17, v22
	v_mul_f32_e32 v12, v12, v22
	v_mul_f32_e32 v13, v13, v22
	v_mul_f32_e32 v14, 0xbfb8aa3b, v14
	v_mul_f32_e32 v10, 0xbfb8aa3b, v10
	v_mul_f32_e32 v15, 0xbfb8aa3b, v15
	v_mul_f32_e32 v11, 0xbfb8aa3b, v11
	v_mul_f32_e32 v16, 0xbfb8aa3b, v16
	v_mul_f32_e32 v17, 0xbfb8aa3b, v17
	v_mul_f32_e32 v12, 0xbfb8aa3b, v12
	v_mul_f32_e32 v13, 0xbfb8aa3b, v13
	v_exp_f32_e32 v14, v14
	v_exp_f32_e32 v10, v10
	v_exp_f32_e32 v15, v15
	v_exp_f32_e32 v11, v11
	v_exp_f32_e32 v16, v16
	v_exp_f32_e32 v17, v17
	v_exp_f32_e32 v12, v12
	v_exp_f32_e32 v13, v13
	v_add_f32_e32 v14, 1.0, v14
	v_add_f32_e32 v20, 1.0, v10
	v_add_f32_e32 v15, 1.0, v15
	v_add_f32_e32 v21, 1.0, v11
	v_add_f32_e32 v16, 1.0, v16
	v_add_f32_e32 v17, 1.0, v17
	v_add_f32_e32 v23, 1.0, v12
	v_add_f32_e32 v24, 1.0, v13
	v_rcp_f32_e32 v10, v14
	v_rcp_f32_e32 v12, v20
	v_rcp_f32_e32 v11, v15
	v_rcp_f32_e32 v13, v21
	v_rcp_f32_e32 v16, v16
	v_rcp_f32_e32 v17, v17
	v_rcp_f32_e32 v20, v23
	v_rcp_f32_e32 v21, v24
	v_and_b32_e32 v51, 0xffff0000, v36
	v_lshlrev_b32_e32 v52, 16, v40
	v_and_b32_e32 v53, 0xffff0000, v40
	v_lshlrev_b32_e32 v34, 16, v35
	v_and_b32_e32 v35, 0xffff0000, v35
	v_lshlrev_b32_e32 v38, 16, v39
	v_and_b32_e32 v39, 0xffff0000, v39
	v_lshlrev_b32_e32 v36, 16, v37
	v_and_b32_e32 v37, 0xffff0000, v37
	v_lshlrev_b32_e32 v18, 16, v41
	v_and_b32_e32 v19, 0xffff0000, v41
	v_pk_fma_f32 v[10:11], v[10:11], v[28:29], v[32:33]
	v_pk_fma_f32 v[14:15], v[12:13], v[50:51], v[52:53]
	v_pk_fma_f32 v[12:13], v[16:17], v[34:35], v[38:39]
	v_pk_fma_f32 v[16:17], v[20:21], v[36:37], v[18:19]
	global_store_dwordx4 v[44:45], v[10:13], off
	global_store_dwordx4 v[44:45], v[14:17], off offset:16
	v_mul_f32_e32 v6, v6, v22
	v_mul_f32_e32 v2, v2, v22
	v_mul_f32_e32 v7, v7, v22
	v_mul_f32_e32 v3, v3, v22
	v_mul_f32_e32 v8, v8, v22
	v_mul_f32_e32 v9, v9, v22
	v_mul_f32_e32 v4, v4, v22
	v_mul_f32_e32 v5, v5, v22
	v_mul_f32_e32 v6, 0xbfb8aa3b, v6
	v_mul_f32_e32 v2, 0xbfb8aa3b, v2
	v_mul_f32_e32 v7, 0xbfb8aa3b, v7
	v_mul_f32_e32 v3, 0xbfb8aa3b, v3
	v_mul_f32_e32 v8, 0xbfb8aa3b, v8
	v_mul_f32_e32 v9, 0xbfb8aa3b, v9
	v_mul_f32_e32 v4, 0xbfb8aa3b, v4
	v_mul_f32_e32 v5, 0xbfb8aa3b, v5
	v_exp_f32_e32 v6, v6
	v_exp_f32_e32 v2, v2
	v_exp_f32_e32 v7, v7
	v_exp_f32_e32 v3, v3
	v_exp_f32_e32 v8, v8
	v_exp_f32_e32 v9, v9
	v_exp_f32_e32 v4, v4
	v_exp_f32_e32 v5, v5
	v_add_f32_e32 v6, 1.0, v6
	v_add_f32_e32 v18, 1.0, v2
	v_add_f32_e32 v7, 1.0, v7
	v_add_f32_e32 v19, 1.0, v3
	v_add_f32_e32 v8, 1.0, v8
	v_add_f32_e32 v9, 1.0, v9
	v_add_f32_e32 v20, 1.0, v4
	v_add_f32_e32 v21, 1.0, v5
	v_rcp_f32_e32 v2, v6
	v_rcp_f32_e32 v4, v18
	v_rcp_f32_e32 v3, v7
	v_rcp_f32_e32 v5, v19
	v_rcp_f32_e32 v8, v8
	v_rcp_f32_e32 v9, v9
	v_rcp_f32_e32 v18, v20
	v_rcp_f32_e32 v19, v21
	s_waitcnt vmcnt(2)
	v_lshlrev_b32_e32 v6, 16, v190
	v_and_b32_e32 v7, 0xffff0000, v190
	v_lshlrev_b32_e32 v22, 16, v192
	v_lshlrev_b32_e32 v20, 16, v194
	v_and_b32_e32 v21, 0xffff0000, v194
	v_and_b32_e32 v23, 0xffff0000, v192
	v_lshlrev_b32_e32 v24, 16, v196
	v_and_b32_e32 v25, 0xffff0000, v196
	v_lshlrev_b32_e32 v10, 16, v191
	v_and_b32_e32 v11, 0xffff0000, v191
	v_lshlrev_b32_e32 v14, 16, v195
	v_and_b32_e32 v15, 0xffff0000, v195
	v_lshlrev_b32_e32 v12, 16, v193
	v_and_b32_e32 v13, 0xffff0000, v193
	v_lshlrev_b32_e32 v16, 16, v197
	v_and_b32_e32 v17, 0xffff0000, v197
	v_pk_fma_f32 v[2:3], v[2:3], v[6:7], v[20:21]
	v_pk_fma_f32 v[6:7], v[4:5], v[22:23], v[24:25]
	v_pk_fma_f32 v[4:5], v[8:9], v[10:11], v[14:15]
	v_pk_fma_f32 v[8:9], v[18:19], v[12:13], v[16:17]
	global_store_dwordx4 v[44:45], v[2:5], off offset:512
	global_store_dwordx4 v[44:45], v[6:9], off offset:528
	s_cbranch_vccnz .LBB0_3282
	s_andn2_b64 vcc, exec, s[4:5]
	s_cbranch_vccnz .LBB0_3281
	s_barrier
	s_branch .LBB0_3281
